# P3/P4/P9 GEMM epilogue stores made nontemporal (streamed outputs should not displace the GEMM operands on-die)
# speedup vs baseline: 1.0255x; 1.0115x over previous
; __device__ __forceinline__ unsigned cvt_pk_bf16(float lo, float hi) { unsigned r; asm volatile("v_cvt_pk_bf16_f32 %0, %1, %2" : "=v"(r) : "v"(lo), "v"(hi)); return r; }
; __device__ __forceinline__ float sigm(float x) { return __builtin_amdgcn_rcpf(1.0f + __expf(-x)); }
;     __device__ __forceinline__ void operator()(const f32x4 (&acc)[2][2][4][2], const Unit& u, int wr, int wc, int fr, int fq) const {
;     ...
;         if (mode == 0 && colt >= g_lo && colt < g_hi) {
;             float lb[2][8];
; #pragma unroll
;             for (int bj = 0; bj < 2; ++bj)
; #pragma unroll
;                 for (int e = 0; e < 8; ++e) { const int c = colt - g_lo + bj * HALF + wc * 32 + 8 * fq + e; lb[bj][e] = sigm(lbl[c] - lbl[2048 + c]); }
;     ...
; #pragma unroll
;         for (int ai = 0; ai < 2; ++ai)
; #pragma unroll
;             for (int m = 0; m < 4; ++m) { bf16_t* rowp = p0 + (size_t)(ai * HALF + m * 16) * rstride;
; #pragma unroll
;                 for (int bj = 0; bj < 2; ++bj) { const f32x4 v0 = acc[ai][bj][m][0], v1 = acc[ai][bj][m][1];
;                     u32x4 w; w.x = cvt_pk_bf16(v0[0], v0[1]); w.y = cvt_pk_bf16(v0[2], v0[3]); w.z = cvt_pk_bf16(v1[0], v1[1]); w.w = cvt_pk_bf16(v1[2], v1[3]);
;                     *(u32x4*)(rowp + bj * bjstride) = w; } }
.LBB0_320:
	s_andn2_b64 vcc, exec, s[96:97]
	s_mul_i32 s34, s55, 0xa0
	s_mul_i32 s87, s55, 0x160
	s_mul_hi_u32 s91, s54, 0x160
	s_mul_i32 s96, s54, 0x160
	s_cbranch_vccnz .LBB0_322
	v_cvt_pk_bf16_f32 v130, v126, v127
	v_cvt_pk_bf16_f32 v131, v128, v129
	v_cvt_pk_bf16_f32 v132, v122, v123
	v_cvt_pk_bf16_f32 v133, v124, v125
	s_lshl_b64 vcc, s[84:85], 1
	global_store_dwordx4 v[156:157], v[130:133], off nt
	v_lshl_add_u64 v[168:169], v[156:157], 0, vcc
	s_lshl_b64 s[8:9], s[54:55], 5
	v_cvt_pk_bf16_f32 v130, v118, v119
	v_cvt_pk_bf16_f32 v131, v120, v121
	v_cvt_pk_bf16_f32 v132, v114, v115
	v_cvt_pk_bf16_f32 v133, v116, v117
	global_store_dwordx4 v[168:169], v[130:133], off nt
	v_lshl_add_u64 v[168:169], v[156:157], 0, s[8:9]
	v_lshl_add_u64 v[170:171], v[168:169], 0, vcc
	v_cvt_pk_bf16_f32 v130, v110, v111
	v_cvt_pk_bf16_f32 v131, v112, v113
	v_cvt_pk_bf16_f32 v132, v106, v107
	v_cvt_pk_bf16_f32 v133, v108, v109
	global_store_dwordx4 v[168:169], v[130:133], off nt
	v_lshl_add_u64 v[168:169], v[168:169], 0, s[8:9]
	s_add_i32 s97, s91, s87
	v_cvt_pk_bf16_f32 v130, v102, v103
	v_cvt_pk_bf16_f32 v131, v104, v105
	v_cvt_pk_bf16_f32 v132, v98, v99
	v_cvt_pk_bf16_f32 v133, v100, v101
	global_store_dwordx4 v[170:171], v[130:133], off nt
	v_lshl_add_u64 v[170:171], v[168:169], 0, vcc
	s_nop 0
	v_cvt_pk_bf16_f32 v130, v94, v95
	v_cvt_pk_bf16_f32 v131, v96, v97
	v_cvt_pk_bf16_f32 v132, v90, v91
	v_cvt_pk_bf16_f32 v133, v92, v93
	global_store_dwordx4 v[168:169], v[130:133], off nt
	v_lshl_add_u64 v[168:169], v[168:169], 0, s[8:9]
	s_nop 0
	v_cvt_pk_bf16_f32 v130, v86, v87
	v_cvt_pk_bf16_f32 v131, v88, v89
	v_cvt_pk_bf16_f32 v132, v82, v83
	v_cvt_pk_bf16_f32 v133, v84, v85
	global_store_dwordx4 v[170:171], v[130:133], off nt
	v_lshl_add_u64 v[170:171], v[168:169], 0, vcc
	s_nop 0
	v_cvt_pk_bf16_f32 v130, v78, v79
	v_cvt_pk_bf16_f32 v131, v80, v81
	v_cvt_pk_bf16_f32 v132, v74, v75
	v_cvt_pk_bf16_f32 v133, v76, v77
	global_store_dwordx4 v[168:169], v[130:133], off nt
	v_mad_u64_u32 v[168:169], s[40:41], s54, v161, v[168:169]
	s_nop 0
	v_cvt_pk_bf16_f32 v130, v70, v71
	v_cvt_pk_bf16_f32 v131, v72, v73
	v_cvt_pk_bf16_f32 v132, v66, v67
	v_cvt_pk_bf16_f32 v133, v68, v69
	global_store_dwordx4 v[170:171], v[130:133], off nt
	v_add_u32_e32 v169, s34, v169
	v_lshl_add_u64 v[170:171], v[168:169], 0, vcc
	v_cvt_pk_bf16_f32 v130, v62, v63
	v_cvt_pk_bf16_f32 v131, v64, v65
	v_cvt_pk_bf16_f32 v132, v58, v59
	v_cvt_pk_bf16_f32 v133, v60, v61
	global_store_dwordx4 v[168:169], v[130:133], off nt
	v_lshl_add_u64 v[168:169], v[168:169], 0, s[8:9]
	s_nop 0
	v_cvt_pk_bf16_f32 v130, v54, v55
	v_cvt_pk_bf16_f32 v131, v56, v57
	v_cvt_pk_bf16_f32 v132, v50, v51
	v_cvt_pk_bf16_f32 v133, v52, v53
	global_store_dwordx4 v[170:171], v[130:133], off nt
	v_lshl_add_u64 v[170:171], v[168:169], 0, vcc
	s_nop 0
	v_cvt_pk_bf16_f32 v130, v46, v47
	v_cvt_pk_bf16_f32 v131, v48, v49
	v_cvt_pk_bf16_f32 v132, v42, v43
	v_cvt_pk_bf16_f32 v133, v44, v45
	global_store_dwordx4 v[168:169], v[130:133], off nt
	v_lshl_add_u64 v[168:169], v[168:169], 0, s[8:9]
	s_nop 0
	v_cvt_pk_bf16_f32 v130, v38, v39
	v_cvt_pk_bf16_f32 v131, v40, v41
	v_cvt_pk_bf16_f32 v132, v34, v35
	v_cvt_pk_bf16_f32 v133, v36, v37
	global_store_dwordx4 v[170:171], v[130:133], off nt
	v_lshl_add_u64 v[170:171], v[168:169], 0, vcc
	s_nop 0
	v_cvt_pk_bf16_f32 v130, v30, v31
	v_cvt_pk_bf16_f32 v131, v32, v33
	v_cvt_pk_bf16_f32 v132, v26, v27
	v_cvt_pk_bf16_f32 v133, v28, v29
	global_store_dwordx4 v[168:169], v[130:133], off nt
	v_lshl_add_u64 v[168:169], v[168:169], 0, s[8:9]
	s_mov_b64 s[8:9], 0
	v_cvt_pk_bf16_f32 v130, v22, v23
	v_cvt_pk_bf16_f32 v131, v24, v25
	v_cvt_pk_bf16_f32 v132, v18, v19
	v_cvt_pk_bf16_f32 v133, v20, v21
	global_store_dwordx4 v[170:171], v[130:133], off nt
	s_nop 1
	v_cvt_pk_bf16_f32 v130, v14, v15
	v_cvt_pk_bf16_f32 v131, v16, v17
	v_cvt_pk_bf16_f32 v132, v10, v11
	v_cvt_pk_bf16_f32 v133, v12, v13
	global_store_dwordx4 v[168:169], v[130:133], off nt
	s_nop 1
	v_cvt_pk_bf16_f32 v130, v6, v7
	v_cvt_pk_bf16_f32 v131, v8, v9
	v_cvt_pk_bf16_f32 v132, v2, v3
	v_cvt_pk_bf16_f32 v133, v4, v5
.LBB0_322:
	s_andn2_b64 vcc, exec, s[8:9]
	s_cbranch_vccnz .LBB0_324
	v_or_b32_e32 v130, s7, v165
	v_subrev_u32_e32 v130, s5, v130
	v_ashrrev_i32_e32 v131, 31, v130
	v_lshl_add_u64 v[184:185], v[130:131], 2, s[66:67]
	s_movk_i32 s7, 0x2000
	v_add_co_u32_e32 v188, vcc, s7, v184
	global_load_dwordx4 v[130:133], v[184:185], off offset:16
	global_load_dwordx4 v[168:171], v[184:185], off
	s_mov_b64 s[8:9], 0x2000
	v_addc_co_u32_e32 v189, vcc, 0, v185, vcc
	v_lshl_add_u64 v[172:173], v[184:185], 0, s[8:9]
	global_load_dwordx4 v[174:177], v[188:189], off
	global_load_dwordx4 v[180:183], v[172:173], off offset:16
	s_mov_b64 s[8:9], 0x2200
	v_max_f32_e32 v126, v126, v126
	v_med3_f32 v126, v126, s17, v162
	v_mul_f32_e32 v126, 0xbfb8aa3b, v126
	v_exp_f32_e32 v126, v126
	v_max_f32_e32 v122, v122, v122
	v_med3_f32 v122, v122, s17, v162
	v_mul_f32_e32 v122, 0xbfb8aa3b, v122
	v_add_f32_e32 v126, 1.0, v126
	v_rcp_f32_e32 v126, v126
	v_max_f32_e32 v123, v123, v123
	v_max_f32_e32 v124, v124, v124
	v_max_f32_e32 v125, v125, v125
	v_exp_f32_e32 v122, v122
	v_med3_f32 v123, v123, s17, v162
	v_med3_f32 v124, v124, s17, v162
	v_med3_f32 v125, v125, s17, v162
	v_mul_f32_e32 v123, 0xbfb8aa3b, v123
	v_mul_f32_e32 v124, 0xbfb8aa3b, v124
	v_mul_f32_e32 v125, 0xbfb8aa3b, v125
	v_exp_f32_e32 v123, v123
	v_exp_f32_e32 v124, v124
	v_exp_f32_e32 v125, v125
	v_add_f32_e32 v122, 1.0, v122
	v_max_f32_e32 v118, v118, v118
	v_add_f32_e32 v123, 1.0, v123
	v_add_f32_e32 v124, 1.0, v124
	v_add_f32_e32 v125, 1.0, v125
	v_med3_f32 v118, v118, s17, v162
	v_rcp_f32_e32 v123, v123
; __device__ __forceinline__ float sigm(float x) { return __builtin_amdgcn_rcpf(1.0f + __expf(-x)); }
;     __device__ __forceinline__ void operator()(const f32x4 (&acc)[2][2][4][2], const Unit& u, int wr, int wc, int fr, int fq) const {
;     ...
;                 for (int e = 0; e < 8; ++e) { const int c = colt - g_lo + bj * HALF + wc * 32 + 8 * fq + e; lb[bj][e] = sigm(lbl[c] - lbl[2048 + c]); }
;     ...
;                         for (int e = 0; e < 8; ++e) { const float v = fminf(fmaxf(acc[ai][bj][m][e >> 2][e & 3], -30.f), 30.f); const float sg = __builtin_amdgcn_rcpf(1.0f + __expf(-v)); o[e] = __log2f(lb[bj][e] + (1.0f - lb[bj][e]) * sg); }
	v_rcp_f32_e32 v124, v124
	v_rcp_f32_e32 v187, v125
	v_mul_f32_e32 v118, 0xbfb8aa3b, v118
	v_exp_f32_e32 v118, v118
	v_max_f32_e32 v116, v116, v116
	v_med3_f32 v116, v116, s17, v162
	v_mul_f32_e32 v116, 0xbfb8aa3b, v116
	v_add_f32_e32 v118, 1.0, v118
	v_rcp_f32_e32 v118, v118
	v_exp_f32_e32 v116, v116
	v_max_f32_e32 v106, v106, v106
	v_med3_f32 v106, v106, s17, v162
	v_mul_f32_e32 v106, 0xbfb8aa3b, v106
	v_add_f32_e32 v116, 1.0, v116
	v_rcp_f32_e32 v116, v116
	v_exp_f32_e32 v106, v106
	v_max_f32_e32 v114, v114, v114
	v_max_f32_e32 v115, v115, v115
	v_med3_f32 v114, v114, s17, v162
	v_add_f32_e32 v106, 1.0, v106
	v_rcp_f32_e32 v106, v106
	v_med3_f32 v115, v115, s17, v162
	v_mul_f32_e32 v114, 0xbfb8aa3b, v114
	v_mul_f32_e32 v115, 0xbfb8aa3b, v115
	v_exp_f32_e32 v114, v114
	v_exp_f32_e32 v115, v115
	s_lshl_b64 vcc, s[84:85], 1
	v_max_f32_e32 v110, v110, v110
	v_add_f32_e32 v114, 1.0, v114
	v_add_f32_e32 v115, 1.0, v115
	v_rcp_f32_e32 v114, v114
	v_rcp_f32_e32 v115, v115
	v_max_f32_e32 v111, v111, v111
	v_max_f32_e32 v112, v112, v112
	v_max_f32_e32 v113, v113, v113
	v_med3_f32 v110, v110, s17, v162
	v_med3_f32 v111, v111, s17, v162
	v_med3_f32 v112, v112, s17, v162
	v_med3_f32 v113, v113, s17, v162
	v_mul_f32_e32 v110, 0xbfb8aa3b, v110
	v_mul_f32_e32 v111, 0xbfb8aa3b, v111
	v_mul_f32_e32 v112, 0xbfb8aa3b, v112
	v_mul_f32_e32 v113, 0xbfb8aa3b, v113
	v_exp_f32_e32 v110, v110
	v_exp_f32_e32 v111, v111
	v_exp_f32_e32 v112, v112
	v_exp_f32_e32 v113, v113
	v_max_f32_e32 v98, v98, v98
	s_waitcnt vmcnt(0)
	v_sub_f32_e32 v167, v168, v174
	v_mul_f32_e32 v167, 0xbfb8aa3b, v167
	v_exp_f32_e32 v167, v167
	v_sub_f32_e32 v130, v130, v180
	v_mul_f32_e32 v130, 0xbfb8aa3b, v130
	v_exp_f32_e32 v130, v130
	v_add_f32_e32 v167, 1.0, v167
	v_rcp_f32_e32 v179, v167
	v_sub_f32_e32 v167, v169, v175
	v_mul_f32_e32 v167, 0xbfb8aa3b, v167
	v_exp_f32_e32 v167, v167
	v_add_f32_e32 v130, 1.0, v130
	v_med3_f32 v98, v98, s17, v162
	v_add_f32_e32 v110, 1.0, v110
	v_add_f32_e32 v167, 1.0, v167
	v_rcp_f32_e32 v175, v167
	v_sub_f32_e32 v167, v170, v176
	v_rcp_f32_e32 v170, v130
	v_sub_f32_e32 v130, v131, v181
	v_mul_f32_e32 v130, 0xbfb8aa3b, v130
	v_exp_f32_e32 v130, v130
	v_mul_f32_e32 v167, 0xbfb8aa3b, v167
	v_exp_f32_e32 v167, v167
	v_add_f32_e32 v111, 1.0, v111
	v_add_f32_e32 v130, 1.0, v130
	v_rcp_f32_e32 v169, v130
	v_sub_f32_e32 v130, v132, v182
	v_mul_f32_e32 v130, 0xbfb8aa3b, v130
	v_exp_f32_e32 v130, v130
	v_add_f32_e32 v167, 1.0, v167
	v_rcp_f32_e32 v173, v167
	v_sub_f32_e32 v167, v171, v177
	v_add_f32_e32 v130, 1.0, v130
	v_rcp_f32_e32 v168, v130
	v_sub_f32_e32 v130, v133, v183
	v_mul_f32_e32 v167, 0xbfb8aa3b, v167
	v_mul_f32_e32 v130, 0xbfb8aa3b, v130
	v_exp_f32_e32 v167, v167
	v_exp_f32_e32 v130, v130
	v_lshl_add_u64 v[176:177], v[184:185], 0, s[8:9]
	v_add_f32_e32 v112, 1.0, v112
	v_add_f32_e32 v167, 1.0, v167
	v_add_f32_e32 v130, 1.0, v130
	v_rcp_f32_e32 v171, v167
	v_rcp_f32_e32 v167, v130
	global_load_dwordx4 v[130:133], v[184:185], off offset:528
	global_load_dwordx4 v[180:183], v[184:185], off offset:512
	s_nop 0
	global_load_dwordx4 v[188:191], v[188:189], off offset:512
	s_nop 0
	global_load_dwordx4 v[192:195], v[176:177], off offset:16
	v_add_f32_e32 v113, 1.0, v113
	v_sub_f32_e32 v125, 1.0, v167
	v_fma_f32 v187, v187, v125, v167
	v_log_f32_e32 v187, v187
	v_mul_f32_e32 v98, 0xbfb8aa3b, v98
	v_rcp_f32_e32 v110, v110
	v_rcp_f32_e32 v111, v111
	v_rcp_f32_e32 v112, v112
	v_rcp_f32_e32 v113, v113
	v_exp_f32_e32 v98, v98
	s_lshl_b64 s[8:9], s[54:55], 5
	v_max_f32_e32 v102, v102, v102
	v_max_f32_e32 v103, v103, v103
	v_add_f32_e32 v98, 1.0, v98
	v_rcp_f32_e32 v98, v98
	v_max_f32_e32 v104, v104, v104
	v_max_f32_e32 v105, v105, v105
	v_med3_f32 v102, v102, s17, v162
	v_med3_f32 v103, v103, s17, v162
	v_med3_f32 v104, v104, s17, v162
	v_med3_f32 v105, v105, s17, v162
	v_mul_f32_e32 v102, 0xbfb8aa3b, v102
	v_mul_f32_e32 v103, 0xbfb8aa3b, v103
	v_mul_f32_e32 v104, 0xbfb8aa3b, v104
	v_mul_f32_e32 v105, 0xbfb8aa3b, v105
	v_exp_f32_e32 v102, v102
	v_exp_f32_e32 v103, v103
	v_exp_f32_e32 v104, v104
	v_exp_f32_e32 v105, v105
	v_max_f32_e32 v90, v90, v90
	v_med3_f32 v90, v90, s17, v162
	v_add_f32_e32 v102, 1.0, v102
	v_add_f32_e32 v103, 1.0, v103
	v_add_f32_e32 v104, 1.0, v104
	v_add_f32_e32 v105, 1.0, v105
	v_mul_f32_e32 v90, 0xbfb8aa3b, v90
	v_rcp_f32_e32 v102, v102
	v_rcp_f32_e32 v103, v103
	v_rcp_f32_e32 v104, v104
	v_rcp_f32_e32 v105, v105
	v_exp_f32_e32 v90, v90
	v_max_f32_e32 v94, v94, v94
	v_max_f32_e32 v95, v95, v95
	v_max_f32_e32 v96, v96, v96
	v_add_f32_e32 v90, 1.0, v90
	v_rcp_f32_e32 v90, v90
	v_max_f32_e32 v97, v97, v97
	v_med3_f32 v94, v94, s17, v162
	v_med3_f32 v95, v95, s17, v162
	v_med3_f32 v96, v96, s17, v162
	v_med3_f32 v97, v97, s17, v162
	v_mul_f32_e32 v94, 0xbfb8aa3b, v94
	v_mul_f32_e32 v95, 0xbfb8aa3b, v95
	v_mul_f32_e32 v96, 0xbfb8aa3b, v96
	v_mul_f32_e32 v97, 0xbfb8aa3b, v97
	v_exp_f32_e32 v94, v94
	v_exp_f32_e32 v95, v95
	v_exp_f32_e32 v96, v96
	v_exp_f32_e32 v97, v97
	v_max_f32_e32 v82, v82, v82
	v_med3_f32 v82, v82, s17, v162
	v_add_f32_e32 v94, 1.0, v94
	v_add_f32_e32 v95, 1.0, v95
	v_add_f32_e32 v96, 1.0, v96
	v_add_f32_e32 v97, 1.0, v97
	v_mul_f32_e32 v82, 0xbfb8aa3b, v82
	v_rcp_f32_e32 v94, v94
	v_rcp_f32_e32 v95, v95
	v_rcp_f32_e32 v96, v96
	v_rcp_f32_e32 v97, v97
	v_exp_f32_e32 v82, v82
	v_max_f32_e32 v86, v86, v86
	v_max_f32_e32 v87, v87, v87
	v_max_f32_e32 v88, v88, v88
	v_add_f32_e32 v82, 1.0, v82
	v_rcp_f32_e32 v82, v82
	v_max_f32_e32 v89, v89, v89
	v_med3_f32 v86, v86, s17, v162
	s_waitcnt vmcnt(1)
	v_sub_f32_e32 v172, v180, v188
	v_mul_f32_e32 v172, 0xbfb8aa3b, v172
	v_exp_f32_e32 v172, v172
	s_waitcnt vmcnt(0)
; __device__ __forceinline__ unsigned cvt_pk_bf16_c(float lo, float hi) { f32x2c v = {lo, hi}; bf16x2c b = __builtin_convertvector(v, bf16x2c); return __builtin_bit_cast(unsigned, b); }
;     __device__ __forceinline__ void operator()(const f32x4 (&acc)[2][2][4][2], const Unit& u, int wr, int wc, int fr, int fq) const {
;     ...
;                     for (int bj = 0; bj < 2; ++bj) { float o[8];
; #pragma unroll
;                         for (int e = 0; e < 8; ++e) { const float v = fminf(fmaxf(acc[ai][bj][m][e >> 2][e & 3], -30.f), 30.f); const float sg = __builtin_amdgcn_rcpf(1.0f + __expf(-v)); o[e] = __log2f(lb[bj][e] + (1.0f - lb[bj][e]) * sg); }
;                         u32x4 w; w.x = cvt_pk_bf16_c(o[0], o[1]); w.y = cvt_pk_bf16_c(o[2], o[3]); w.z = cvt_pk_bf16_c(o[4], o[5]); w.w = cvt_pk_bf16_c(o[6], o[7]);
;                         *(u32x4*)(rowp + bj * bjstride) = w; } }
	v_sub_f32_e32 v130, v130, v192
	v_mul_f32_e32 v130, 0xbfb8aa3b, v130
	v_exp_f32_e32 v130, v130
	v_add_f32_e32 v172, 1.0, v172
	v_rcp_f32_e32 v178, v172
	v_sub_f32_e32 v172, v181, v189
	v_mul_f32_e32 v172, 0xbfb8aa3b, v172
	v_exp_f32_e32 v172, v172
	v_add_f32_e32 v130, 1.0, v130
	v_rcp_f32_e32 v177, v130
	v_sub_f32_e32 v130, v131, v193
	v_sub_f32_e32 v131, v132, v194
	v_sub_f32_e32 v132, v133, v195
	v_sub_f32_e32 v133, 1.0, v179
	v_add_f32_e32 v172, 1.0, v172
	v_fma_f32 v126, v126, v133, v179
	v_rcp_f32_e32 v174, v172
	v_sub_f32_e32 v172, v182, v190
	v_log_f32_e32 v182, v126
	v_max_f32_e32 v126, v127, v127
	v_med3_f32 v126, v126, s17, v162
	v_mul_f32_e32 v126, 0xbfb8aa3b, v126
	v_exp_f32_e32 v126, v126
	v_mul_f32_e32 v172, 0xbfb8aa3b, v172
	v_exp_f32_e32 v172, v172
	v_sub_f32_e32 v127, 1.0, v175
	v_add_f32_e32 v126, 1.0, v126
	v_rcp_f32_e32 v126, v126
	v_add_f32_e32 v172, 1.0, v172
	v_rcp_f32_e32 v176, v172
	v_sub_f32_e32 v172, v183, v191
	v_fma_f32 v126, v126, v127, v175
	v_log_f32_e32 v183, v126
	v_max_f32_e32 v126, v128, v128
	v_med3_f32 v126, v126, s17, v162
	v_mul_f32_e32 v126, 0xbfb8aa3b, v126
	v_exp_f32_e32 v126, v126
	v_sub_f32_e32 v180, 1.0, v171
	v_sub_f32_e32 v181, 1.0, v169
	v_fma_f32 v123, v123, v181, v169
	v_add_f32_e32 v126, 1.0, v126
	v_rcp_f32_e32 v128, v126
	v_sub_f32_e32 v126, 1.0, v173
	v_log_f32_e32 v123, v123
	v_cvt_pk_bf16_f32 v182, v182, v183
	v_fma_f32 v128, v128, v126, v173
	v_log_f32_e32 v184, v128
	v_max_f32_e32 v128, v129, v129
	v_med3_f32 v128, v128, s17, v162
	v_mul_f32_e32 v128, 0xbfb8aa3b, v128
	v_exp_f32_e32 v128, v128
	v_mul_f32_e32 v131, 0xbfb8aa3b, v131
	v_exp_f32_e32 v131, v131
	v_mul_f32_e32 v172, 0xbfb8aa3b, v172
	v_add_f32_e32 v128, 1.0, v128
	v_rcp_f32_e32 v128, v128
	v_add_f32_e32 v131, 1.0, v131
	v_rcp_f32_e32 v131, v131
	v_mul_f32_e32 v132, 0xbfb8aa3b, v132
	v_fma_f32 v128, v128, v180, v171
	v_log_f32_e32 v129, v128
	v_rcp_f32_e32 v128, v122
	v_sub_f32_e32 v122, 1.0, v170
	v_exp_f32_e32 v172, v172
	v_cvt_pk_bf16_f32 v183, v184, v129
	v_fma_f32 v128, v128, v122, v170
	v_log_f32_e32 v185, v128
	v_sub_f32_e32 v128, 1.0, v168
	v_fma_f32 v124, v124, v128, v168
	v_log_f32_e32 v124, v124
	v_cvt_pk_bf16_f32 v184, v185, v123
	v_sub_f32_e32 v123, 1.0, v174
	v_exp_f32_e32 v132, v132
	v_cvt_pk_bf16_f32 v185, v124, v187
	v_sub_f32_e32 v124, 1.0, v178
	v_fma_f32 v118, v118, v124, v178
	global_store_dwordx4 v[156:157], v[182:185], off nt
	v_add_f32_e32 v172, 1.0, v172
	v_add_f32_e32 v132, 1.0, v132
	v_log_f32_e32 v182, v118
	v_max_f32_e32 v118, v119, v119
	v_med3_f32 v118, v118, s17, v162
	v_mul_f32_e32 v118, 0xbfb8aa3b, v118
	v_exp_f32_e32 v118, v118
	v_sub_f32_e32 v119, 1.0, v176
	v_rcp_f32_e32 v172, v172
	v_rcp_f32_e32 v132, v132
	v_add_f32_e32 v118, 1.0, v118
	v_rcp_f32_e32 v118, v118
	v_mul_f32_e32 v130, 0xbfb8aa3b, v130
	v_exp_f32_e32 v130, v130
	v_fma_f32 v106, v106, v122, v170
	v_fma_f32 v118, v118, v123, v174
	v_log_f32_e32 v183, v118
	v_max_f32_e32 v118, v120, v120
	v_med3_f32 v118, v118, s17, v162
	v_mul_f32_e32 v118, 0xbfb8aa3b, v118
	v_exp_f32_e32 v118, v118
	v_sub_f32_e32 v120, 1.0, v131
	v_fma_f32 v116, v116, v120, v131
	v_log_f32_e32 v187, v116
	v_add_f32_e32 v118, 1.0, v118
	v_rcp_f32_e32 v118, v118
	v_max_f32_e32 v116, v117, v117
	v_med3_f32 v116, v116, s17, v162
	v_mul_f32_e32 v116, 0xbfb8aa3b, v116
	v_fma_f32 v118, v118, v119, v176
	v_log_f32_e32 v184, v118
	v_max_f32_e32 v118, v121, v121
	v_med3_f32 v118, v118, s17, v162
	v_mul_f32_e32 v118, 0xbfb8aa3b, v118
	v_exp_f32_e32 v118, v118
	v_exp_f32_e32 v116, v116
	v_sub_f32_e32 v121, 1.0, v172
	v_cvt_pk_bf16_f32 v182, v182, v183
	v_add_f32_e32 v118, 1.0, v118
	v_add_f32_e32 v116, 1.0, v116
	v_rcp_f32_e32 v118, v118
	v_rcp_f32_e32 v117, v116
	v_sub_f32_e32 v116, 1.0, v132
	v_add_f32_e32 v130, 1.0, v130
	v_fma_f32 v118, v118, v121, v172
	v_fma_f32 v117, v117, v116, v132
	v_log_f32_e32 v185, v118
	v_log_f32_e32 v117, v117
	v_rcp_f32_e32 v130, v130
	v_sub_f32_e32 v118, 1.0, v177
	v_cvt_pk_bf16_f32 v183, v184, v185
	v_cvt_pk_bf16_f32 v185, v187, v117
	v_log_f32_e32 v117, v106
	v_max_f32_e32 v106, v107, v107
	v_med3_f32 v106, v106, s17, v162
	v_mul_f32_e32 v106, 0xbfb8aa3b, v106
	v_exp_f32_e32 v106, v106
	v_sub_f32_e32 v129, 1.0, v130
	v_fma_f32 v114, v114, v118, v177
	v_fma_f32 v115, v115, v129, v130
	v_add_f32_e32 v106, 1.0, v106
	v_log_f32_e32 v114, v114
	v_log_f32_e32 v115, v115
	v_rcp_f32_e32 v106, v106
	v_fma_f32 v110, v110, v133, v179
	v_fma_f32 v111, v111, v127, v175
	v_cvt_pk_bf16_f32 v184, v114, v115
	v_lshl_add_u64 v[114:115], v[156:157], 0, vcc
	v_fma_f32 v106, v106, v181, v169
	global_store_dwordx4 v[114:115], v[182:185], off nt
	v_fma_f32 v112, v112, v126, v173
	v_fma_f32 v113, v113, v180, v171
	v_log_f32_e32 v182, v106
	v_max_f32_e32 v106, v108, v108
	v_med3_f32 v106, v106, s17, v162
	v_mul_f32_e32 v106, 0xbfb8aa3b, v106
	v_exp_f32_e32 v106, v106
	v_log_f32_e32 v110, v110
	v_log_f32_e32 v111, v111
	v_log_f32_e32 v112, v112
	v_add_f32_e32 v106, 1.0, v106
	v_rcp_f32_e32 v106, v106
	v_log_f32_e32 v113, v113
	v_lshl_add_u64 v[114:115], v[156:157], 0, s[8:9]
	v_cvt_pk_bf16_f32 v108, v117, v182
	v_fma_f32 v106, v106, v128, v168
	v_log_f32_e32 v183, v106
	v_max_f32_e32 v106, v109, v109
	v_med3_f32 v106, v106, s17, v162
	v_mul_f32_e32 v106, 0xbfb8aa3b, v106
	v_exp_f32_e32 v106, v106
	v_cvt_pk_bf16_f32 v107, v112, v113
	v_fma_f32 v98, v98, v118, v177
	v_fma_f32 v102, v102, v124, v178
	v_add_f32_e32 v106, 1.0, v106
	v_rcp_f32_e32 v106, v106
	v_fma_f32 v103, v103, v123, v174
	v_fma_f32 v104, v104, v119, v176
	v_fma_f32 v105, v105, v121, v172
	v_fma_f32 v106, v106, v125, v167
	v_log_f32_e32 v109, v106
	v_cvt_pk_bf16_f32 v106, v110, v111
; __device__ __forceinline__ unsigned cvt_pk_bf16_c(float lo, float hi) { f32x2c v = {lo, hi}; bf16x2c b = __builtin_convertvector(v, bf16x2c); return __builtin_bit_cast(unsigned, b); }
;     __device__ __forceinline__ void operator()(const f32x4 (&acc)[2][2][4][2], const Unit& u, int wr, int wc, int fr, int fq) const {
;     ...
;                     for (int bj = 0; bj < 2; ++bj) { float o[8];
; #pragma unroll
;                         for (int e = 0; e < 8; ++e) { const float v = fminf(fmaxf(acc[ai][bj][m][e >> 2][e & 3], -30.f), 30.f); const float sg = __builtin_amdgcn_rcpf(1.0f + __expf(-v)); o[e] = __log2f(lb[bj][e] + (1.0f - lb[bj][e]) * sg); }
;                         u32x4 w; w.x = cvt_pk_bf16_c(o[0], o[1]); w.y = cvt_pk_bf16_c(o[2], o[3]); w.z = cvt_pk_bf16_c(o[4], o[5]); w.w = cvt_pk_bf16_c(o[6], o[7]);
;                         *(u32x4*)(rowp + bj * bjstride) = w; } }
	v_log_f32_e32 v102, v102
	v_log_f32_e32 v103, v103
	v_cvt_pk_bf16_f32 v109, v183, v109
	global_store_dwordx4 v[114:115], v[106:109], off nt
	v_log_f32_e32 v104, v104
	v_log_f32_e32 v105, v105
	v_log_f32_e32 v106, v98
	v_max_f32_e32 v98, v99, v99
	v_med3_f32 v98, v98, s17, v162
	v_mul_f32_e32 v98, 0xbfb8aa3b, v98
	v_exp_f32_e32 v98, v98
	v_cvt_pk_bf16_f32 v99, v104, v105
	v_fma_f32 v90, v90, v122, v170
	v_fma_f32 v94, v94, v133, v179
	v_add_f32_e32 v98, 1.0, v98
	v_rcp_f32_e32 v98, v98
	v_fma_f32 v95, v95, v127, v175
	v_fma_f32 v96, v96, v126, v173
	v_fma_f32 v97, v97, v180, v171
	v_fma_f32 v98, v98, v129, v130
	v_log_f32_e32 v107, v98
	v_max_f32_e32 v98, v100, v100
	v_med3_f32 v98, v98, s17, v162
	v_mul_f32_e32 v98, 0xbfb8aa3b, v98
	v_exp_f32_e32 v98, v98
	v_cvt_pk_bf16_f32 v100, v106, v107
	v_log_f32_e32 v94, v94
	v_log_f32_e32 v95, v95
	v_add_f32_e32 v98, 1.0, v98
	v_rcp_f32_e32 v98, v98
	v_log_f32_e32 v96, v96
	v_log_f32_e32 v97, v97
	v_fma_f32 v82, v82, v118, v177
	v_fma_f32 v98, v98, v120, v131
	v_log_f32_e32 v108, v98
	v_max_f32_e32 v98, v101, v101
	v_med3_f32 v98, v98, s17, v162
	v_mul_f32_e32 v98, 0xbfb8aa3b, v98
	v_exp_f32_e32 v98, v98
	v_med3_f32 v87, v87, s17, v162
	v_med3_f32 v88, v88, s17, v162
	v_med3_f32 v89, v89, s17, v162
	v_add_f32_e32 v98, 1.0, v98
	v_rcp_f32_e32 v98, v98
	v_mul_f32_e32 v86, 0xbfb8aa3b, v86
	v_mul_f32_e32 v87, 0xbfb8aa3b, v87
	v_mul_f32_e32 v88, 0xbfb8aa3b, v88
	v_fma_f32 v98, v98, v116, v132
	v_log_f32_e32 v101, v98
	v_cvt_pk_bf16_f32 v98, v102, v103
	v_lshl_add_u64 v[102:103], v[114:115], 0, vcc
	v_mul_f32_e32 v89, 0xbfb8aa3b, v89
	v_cvt_pk_bf16_f32 v101, v108, v101
	global_store_dwordx4 v[102:103], v[98:101], off nt
	v_exp_f32_e32 v86, v86
	v_exp_f32_e32 v87, v87
	v_log_f32_e32 v100, v90
	v_max_f32_e32 v90, v91, v91
	v_med3_f32 v90, v90, s17, v162
	v_mul_f32_e32 v90, 0xbfb8aa3b, v90
	v_exp_f32_e32 v90, v90
	v_lshl_add_u64 v[98:99], v[114:115], 0, s[8:9]
	v_cvt_pk_bf16_f32 v91, v96, v97
	v_exp_f32_e32 v88, v88
	v_add_f32_e32 v90, 1.0, v90
	v_rcp_f32_e32 v90, v90
	v_exp_f32_e32 v89, v89
	v_max_f32_e32 v74, v74, v74
	v_med3_f32 v74, v74, s17, v162
	v_fma_f32 v90, v90, v181, v169
	v_log_f32_e32 v101, v90
	v_max_f32_e32 v90, v92, v92
	v_med3_f32 v90, v90, s17, v162
	v_mul_f32_e32 v90, 0xbfb8aa3b, v90
	v_exp_f32_e32 v90, v90
	v_cvt_pk_bf16_f32 v92, v100, v101
	v_add_f32_e32 v86, 1.0, v86
	v_add_f32_e32 v87, 1.0, v87
	v_add_f32_e32 v90, 1.0, v90
	v_rcp_f32_e32 v90, v90
	v_add_f32_e32 v88, 1.0, v88
	v_add_f32_e32 v89, 1.0, v89
	v_mul_f32_e32 v74, 0xbfb8aa3b, v74
	v_fma_f32 v90, v90, v128, v168
	v_log_f32_e32 v102, v90
	v_max_f32_e32 v90, v93, v93
	v_med3_f32 v90, v90, s17, v162
	v_mul_f32_e32 v90, 0xbfb8aa3b, v90
	v_exp_f32_e32 v90, v90
	v_rcp_f32_e32 v86, v86
	v_rcp_f32_e32 v87, v87
	v_rcp_f32_e32 v88, v88
	v_add_f32_e32 v90, 1.0, v90
	v_rcp_f32_e32 v90, v90
	v_rcp_f32_e32 v89, v89
	v_exp_f32_e32 v74, v74
	v_fma_f32 v86, v86, v124, v178
	v_fma_f32 v90, v90, v125, v167
	v_log_f32_e32 v93, v90
	v_cvt_pk_bf16_f32 v90, v94, v95
	v_fma_f32 v87, v87, v123, v174
	v_fma_f32 v88, v88, v119, v176
	v_cvt_pk_bf16_f32 v93, v102, v93
	global_store_dwordx4 v[98:99], v[90:93], off nt
	v_fma_f32 v89, v89, v121, v172
	v_add_f32_e32 v74, 1.0, v74
	v_log_f32_e32 v90, v82
	v_max_f32_e32 v82, v83, v83
	v_med3_f32 v82, v82, s17, v162
	v_mul_f32_e32 v82, 0xbfb8aa3b, v82
	v_exp_f32_e32 v82, v82
	v_log_f32_e32 v86, v86
	v_log_f32_e32 v87, v87
	v_log_f32_e32 v88, v88
	v_add_f32_e32 v82, 1.0, v82
	v_rcp_f32_e32 v82, v82
	v_log_f32_e32 v89, v89
	v_rcp_f32_e32 v74, v74
	v_max_f32_e32 v78, v78, v78
	v_fma_f32 v82, v82, v129, v130
	v_log_f32_e32 v91, v82
	v_max_f32_e32 v82, v84, v84
	v_med3_f32 v82, v82, s17, v162
	v_mul_f32_e32 v82, 0xbfb8aa3b, v82
	v_exp_f32_e32 v82, v82
	v_cvt_pk_bf16_f32 v83, v88, v89
	v_cvt_pk_bf16_f32 v84, v90, v91
	v_fma_f32 v74, v74, v122, v170
	v_add_f32_e32 v82, 1.0, v82
	v_rcp_f32_e32 v82, v82
	v_max_f32_e32 v79, v79, v79
	v_max_f32_e32 v80, v80, v80
	v_max_f32_e32 v81, v81, v81
	v_fma_f32 v82, v82, v120, v131
	v_log_f32_e32 v92, v82
	v_max_f32_e32 v82, v85, v85
	v_med3_f32 v82, v82, s17, v162
	v_mul_f32_e32 v82, 0xbfb8aa3b, v82
	v_exp_f32_e32 v82, v82
	v_med3_f32 v78, v78, s17, v162
	v_med3_f32 v79, v79, s17, v162
	v_med3_f32 v80, v80, s17, v162
	v_add_f32_e32 v82, 1.0, v82
	v_rcp_f32_e32 v82, v82
	v_med3_f32 v81, v81, s17, v162
	v_mul_f32_e32 v78, 0xbfb8aa3b, v78
	v_mul_f32_e32 v79, 0xbfb8aa3b, v79
	v_fma_f32 v82, v82, v116, v132
	v_log_f32_e32 v85, v82
	v_cvt_pk_bf16_f32 v82, v86, v87
	v_lshl_add_u64 v[86:87], v[98:99], 0, vcc
	v_mul_f32_e32 v80, 0xbfb8aa3b, v80
	v_cvt_pk_bf16_f32 v85, v92, v85
	global_store_dwordx4 v[86:87], v[82:85], off nt
	v_mul_f32_e32 v81, 0xbfb8aa3b, v81
	v_exp_f32_e32 v78, v78
	v_log_f32_e32 v84, v74
	v_max_f32_e32 v74, v75, v75
	v_med3_f32 v74, v74, s17, v162
	v_mul_f32_e32 v74, 0xbfb8aa3b, v74
	v_exp_f32_e32 v74, v74
	v_exp_f32_e32 v79, v79
	v_exp_f32_e32 v80, v80
	v_exp_f32_e32 v81, v81
	v_add_f32_e32 v74, 1.0, v74
	v_rcp_f32_e32 v74, v74
	v_max_f32_e32 v66, v66, v66
	v_med3_f32 v66, v66, s17, v162
	v_add_f32_e32 v78, 1.0, v78
	v_fma_f32 v74, v74, v181, v169
	v_log_f32_e32 v85, v74
	v_max_f32_e32 v74, v76, v76
	v_med3_f32 v74, v74, s17, v162
	v_mul_f32_e32 v74, 0xbfb8aa3b, v74
	v_exp_f32_e32 v74, v74
	v_add_f32_e32 v79, 1.0, v79
	v_add_f32_e32 v80, 1.0, v80
	v_add_f32_e32 v81, 1.0, v81
	v_add_f32_e32 v74, 1.0, v74
	v_rcp_f32_e32 v74, v74
	v_mul_f32_e32 v66, 0xbfb8aa3b, v66
	v_rcp_f32_e32 v78, v78
	v_rcp_f32_e32 v79, v79
	v_fma_f32 v74, v74, v128, v168
	v_log_f32_e32 v86, v74
	v_max_f32_e32 v74, v77, v77
	v_med3_f32 v74, v74, s17, v162
	v_mul_f32_e32 v74, 0xbfb8aa3b, v74
; __device__ __forceinline__ unsigned cvt_pk_bf16_c(float lo, float hi) { f32x2c v = {lo, hi}; bf16x2c b = __builtin_convertvector(v, bf16x2c); return __builtin_bit_cast(unsigned, b); }
;     __device__ __forceinline__ void operator()(const f32x4 (&acc)[2][2][4][2], const Unit& u, int wr, int wc, int fr, int fq) const {
;     ...
;                     for (int bj = 0; bj < 2; ++bj) { float o[8];
; #pragma unroll
;                         for (int e = 0; e < 8; ++e) { const float v = fminf(fmaxf(acc[ai][bj][m][e >> 2][e & 3], -30.f), 30.f); const float sg = __builtin_amdgcn_rcpf(1.0f + __expf(-v)); o[e] = __log2f(lb[bj][e] + (1.0f - lb[bj][e]) * sg); }
;                         u32x4 w; w.x = cvt_pk_bf16_c(o[0], o[1]); w.y = cvt_pk_bf16_c(o[2], o[3]); w.z = cvt_pk_bf16_c(o[4], o[5]); w.w = cvt_pk_bf16_c(o[6], o[7]);
;                         *(u32x4*)(rowp + bj * bjstride) = w; } }
	v_exp_f32_e32 v74, v74
	v_rcp_f32_e32 v80, v80
	v_rcp_f32_e32 v81, v81
	v_exp_f32_e32 v66, v66
	v_add_f32_e32 v74, 1.0, v74
	v_rcp_f32_e32 v74, v74
	v_fma_f32 v78, v78, v133, v179
	v_fma_f32 v79, v79, v127, v175
	v_fma_f32 v80, v80, v126, v173
	v_fma_f32 v81, v81, v180, v171
	v_fma_f32 v74, v74, v125, v167
	v_add_f32_e32 v66, 1.0, v66
	v_log_f32_e32 v78, v78
	v_log_f32_e32 v79, v79
	v_log_f32_e32 v80, v80
	v_log_f32_e32 v81, v81
	v_log_f32_e32 v77, v74
	v_rcp_f32_e32 v66, v66
	v_lshl_add_u64 v[82:83], v[98:99], 0, s[8:9]
	v_cvt_pk_bf16_f32 v74, v78, v79
	v_cvt_pk_bf16_f32 v75, v80, v81
	v_cvt_pk_bf16_f32 v76, v84, v85
	v_cvt_pk_bf16_f32 v77, v86, v77
	v_fma_f32 v66, v66, v118, v177
	global_store_dwordx4 v[82:83], v[74:77], off nt
	v_max_f32_e32 v70, v70, v70
	v_max_f32_e32 v71, v71, v71
	v_log_f32_e32 v74, v66
	v_max_f32_e32 v66, v67, v67
	v_med3_f32 v66, v66, s17, v162
	v_mul_f32_e32 v66, 0xbfb8aa3b, v66
	v_exp_f32_e32 v66, v66
	v_max_f32_e32 v72, v72, v72
	v_max_f32_e32 v73, v73, v73
	v_med3_f32 v70, v70, s17, v162
	v_add_f32_e32 v66, 1.0, v66
	v_rcp_f32_e32 v66, v66
	v_med3_f32 v71, v71, s17, v162
	v_med3_f32 v72, v72, s17, v162
	v_med3_f32 v73, v73, s17, v162
	v_fma_f32 v66, v66, v129, v130
	v_log_f32_e32 v75, v66
	v_max_f32_e32 v66, v68, v68
	v_med3_f32 v66, v66, s17, v162
	v_mul_f32_e32 v66, 0xbfb8aa3b, v66
	v_exp_f32_e32 v66, v66
	v_mul_f32_e32 v70, 0xbfb8aa3b, v70
	v_mul_f32_e32 v71, 0xbfb8aa3b, v71
	v_mul_f32_e32 v72, 0xbfb8aa3b, v72
	v_add_f32_e32 v66, 1.0, v66
	v_rcp_f32_e32 v66, v66
	v_mul_f32_e32 v73, 0xbfb8aa3b, v73
	v_exp_f32_e32 v70, v70
	v_exp_f32_e32 v71, v71
	v_fma_f32 v66, v66, v120, v131
	v_log_f32_e32 v76, v66
	v_max_f32_e32 v66, v69, v69
	v_med3_f32 v66, v66, s17, v162
	v_mul_f32_e32 v66, 0xbfb8aa3b, v66
	v_exp_f32_e32 v72, v72
	v_exp_f32_e32 v73, v73
	v_exp_f32_e32 v66, v66
	v_max_f32_e32 v58, v58, v58
	v_med3_f32 v58, v58, s17, v162
	v_add_f32_e32 v70, 1.0, v70
	v_add_f32_e32 v71, 1.0, v71
	v_add_f32_e32 v72, 1.0, v72
	v_add_f32_e32 v73, 1.0, v73
	v_add_f32_e32 v66, 1.0, v66
	v_mul_f32_e32 v58, 0xbfb8aa3b, v58
	v_rcp_f32_e32 v70, v70
	v_rcp_f32_e32 v71, v71
	v_rcp_f32_e32 v72, v72
	v_rcp_f32_e32 v73, v73
	v_rcp_f32_e32 v66, v66
	v_exp_f32_e32 v58, v58
	v_fma_f32 v70, v70, v124, v178
	v_fma_f32 v71, v71, v123, v174
	v_fma_f32 v72, v72, v119, v176
	v_fma_f32 v73, v73, v121, v172
	v_fma_f32 v66, v66, v116, v132
	v_add_f32_e32 v58, 1.0, v58
	v_log_f32_e32 v70, v70
	v_log_f32_e32 v71, v71
	v_log_f32_e32 v72, v72
	v_log_f32_e32 v73, v73
	v_log_f32_e32 v69, v66
	v_rcp_f32_e32 v58, v58
	v_cvt_pk_bf16_f32 v66, v70, v71
	v_cvt_pk_bf16_f32 v67, v72, v73
	v_cvt_pk_bf16_f32 v68, v74, v75
	v_cvt_pk_bf16_f32 v69, v76, v69
	v_lshl_add_u64 v[70:71], v[82:83], 0, vcc
	v_fma_f32 v58, v58, v122, v170
	global_store_dwordx4 v[70:71], v[66:69], off nt
	v_max_f32_e32 v62, v62, v62
	v_max_f32_e32 v63, v63, v63
	v_log_f32_e32 v68, v58
	v_max_f32_e32 v58, v59, v59
	v_med3_f32 v58, v58, s17, v162
	v_mul_f32_e32 v58, 0xbfb8aa3b, v58
	v_exp_f32_e32 v58, v58
	v_max_f32_e32 v64, v64, v64
	v_max_f32_e32 v65, v65, v65
	v_med3_f32 v62, v62, s17, v162
	v_add_f32_e32 v58, 1.0, v58
	v_rcp_f32_e32 v58, v58
	v_med3_f32 v63, v63, s17, v162
	v_med3_f32 v64, v64, s17, v162
	v_med3_f32 v65, v65, s17, v162
	v_fma_f32 v58, v58, v181, v169
	v_log_f32_e32 v69, v58
	v_max_f32_e32 v58, v60, v60
	v_med3_f32 v58, v58, s17, v162
	v_mul_f32_e32 v58, 0xbfb8aa3b, v58
	v_exp_f32_e32 v58, v58
	v_mul_f32_e32 v62, 0xbfb8aa3b, v62
	v_mul_f32_e32 v63, 0xbfb8aa3b, v63
	v_mul_f32_e32 v64, 0xbfb8aa3b, v64
	v_add_f32_e32 v58, 1.0, v58
	v_rcp_f32_e32 v58, v58
	v_mul_f32_e32 v65, 0xbfb8aa3b, v65
	v_exp_f32_e32 v62, v62
	v_exp_f32_e32 v63, v63
	v_fma_f32 v58, v58, v128, v168
	v_log_f32_e32 v70, v58
	v_max_f32_e32 v58, v61, v61
	v_med3_f32 v58, v58, s17, v162
	v_mul_f32_e32 v58, 0xbfb8aa3b, v58
	v_exp_f32_e32 v64, v64
	v_exp_f32_e32 v65, v65
	v_exp_f32_e32 v58, v58
	v_max_f32_e32 v50, v50, v50
	v_med3_f32 v50, v50, s17, v162
	v_add_f32_e32 v62, 1.0, v62
	v_add_f32_e32 v63, 1.0, v63
	v_add_f32_e32 v64, 1.0, v64
	v_add_f32_e32 v65, 1.0, v65
	v_add_f32_e32 v58, 1.0, v58
	v_mul_f32_e32 v50, 0xbfb8aa3b, v50
	v_rcp_f32_e32 v62, v62
	v_rcp_f32_e32 v63, v63
	v_rcp_f32_e32 v64, v64
	v_rcp_f32_e32 v65, v65
	v_rcp_f32_e32 v58, v58
	v_exp_f32_e32 v50, v50
	v_fma_f32 v62, v62, v133, v179
	v_fma_f32 v63, v63, v127, v175
	v_fma_f32 v64, v64, v126, v173
	v_fma_f32 v65, v65, v180, v171
	v_fma_f32 v58, v58, v125, v167
	v_add_f32_e32 v50, 1.0, v50
	v_log_f32_e32 v62, v62
	v_log_f32_e32 v63, v63
	v_log_f32_e32 v64, v64
	v_log_f32_e32 v65, v65
	v_log_f32_e32 v61, v58
	v_rcp_f32_e32 v50, v50
	v_mad_u64_u32 v[66:67], s[40:41], s54, v161, v[82:83]
	v_add_u32_e32 v67, s34, v67
	v_cvt_pk_bf16_f32 v58, v62, v63
	v_cvt_pk_bf16_f32 v59, v64, v65
	v_cvt_pk_bf16_f32 v60, v68, v69
	v_cvt_pk_bf16_f32 v61, v70, v61
	v_fma_f32 v50, v50, v118, v177
	global_store_dwordx4 v[66:67], v[58:61], off nt
	v_max_f32_e32 v54, v54, v54
	v_max_f32_e32 v55, v55, v55
	v_log_f32_e32 v58, v50
	v_max_f32_e32 v50, v51, v51
	v_med3_f32 v50, v50, s17, v162
	v_mul_f32_e32 v50, 0xbfb8aa3b, v50
	v_exp_f32_e32 v50, v50
	v_max_f32_e32 v56, v56, v56
	v_max_f32_e32 v57, v57, v57
	v_med3_f32 v54, v54, s17, v162
	v_add_f32_e32 v50, 1.0, v50
	v_rcp_f32_e32 v50, v50
	v_med3_f32 v55, v55, s17, v162
	v_med3_f32 v56, v56, s17, v162
	v_med3_f32 v57, v57, s17, v162
	v_fma_f32 v50, v50, v129, v130
	v_log_f32_e32 v59, v50
	v_max_f32_e32 v50, v52, v52
	v_med3_f32 v50, v50, s17, v162
	v_mul_f32_e32 v50, 0xbfb8aa3b, v50
	v_exp_f32_e32 v50, v50
	v_mul_f32_e32 v54, 0xbfb8aa3b, v54
	v_mul_f32_e32 v55, 0xbfb8aa3b, v55
	v_mul_f32_e32 v56, 0xbfb8aa3b, v56
; __device__ __forceinline__ unsigned cvt_pk_bf16_c(float lo, float hi) { f32x2c v = {lo, hi}; bf16x2c b = __builtin_convertvector(v, bf16x2c); return __builtin_bit_cast(unsigned, b); }
;     __device__ __forceinline__ void operator()(const f32x4 (&acc)[2][2][4][2], const Unit& u, int wr, int wc, int fr, int fq) const {
;     ...
;                     for (int bj = 0; bj < 2; ++bj) { float o[8];
; #pragma unroll
;                         for (int e = 0; e < 8; ++e) { const float v = fminf(fmaxf(acc[ai][bj][m][e >> 2][e & 3], -30.f), 30.f); const float sg = __builtin_amdgcn_rcpf(1.0f + __expf(-v)); o[e] = __log2f(lb[bj][e] + (1.0f - lb[bj][e]) * sg); }
;                         u32x4 w; w.x = cvt_pk_bf16_c(o[0], o[1]); w.y = cvt_pk_bf16_c(o[2], o[3]); w.z = cvt_pk_bf16_c(o[4], o[5]); w.w = cvt_pk_bf16_c(o[6], o[7]);
;                         *(u32x4*)(rowp + bj * bjstride) = w; } }
	v_add_f32_e32 v50, 1.0, v50
	v_rcp_f32_e32 v50, v50
	v_mul_f32_e32 v57, 0xbfb8aa3b, v57
	v_exp_f32_e32 v54, v54
	v_exp_f32_e32 v55, v55
	v_fma_f32 v50, v50, v120, v131
	v_log_f32_e32 v60, v50
	v_max_f32_e32 v50, v53, v53
	v_med3_f32 v50, v50, s17, v162
	v_mul_f32_e32 v50, 0xbfb8aa3b, v50
	v_exp_f32_e32 v56, v56
	v_exp_f32_e32 v57, v57
	v_exp_f32_e32 v50, v50
	v_max_f32_e32 v42, v42, v42
	v_med3_f32 v42, v42, s17, v162
	v_add_f32_e32 v54, 1.0, v54
	v_add_f32_e32 v55, 1.0, v55
	v_add_f32_e32 v56, 1.0, v56
	v_add_f32_e32 v57, 1.0, v57
	v_add_f32_e32 v50, 1.0, v50
	v_mul_f32_e32 v42, 0xbfb8aa3b, v42
	v_rcp_f32_e32 v54, v54
	v_rcp_f32_e32 v55, v55
	v_rcp_f32_e32 v56, v56
	v_rcp_f32_e32 v57, v57
	v_rcp_f32_e32 v50, v50
	v_exp_f32_e32 v42, v42
	v_fma_f32 v54, v54, v124, v178
	v_fma_f32 v55, v55, v123, v174
	v_fma_f32 v56, v56, v119, v176
	v_fma_f32 v57, v57, v121, v172
	v_fma_f32 v50, v50, v116, v132
	v_add_f32_e32 v42, 1.0, v42
	v_log_f32_e32 v54, v54
	v_log_f32_e32 v55, v55
	v_log_f32_e32 v56, v56
	v_log_f32_e32 v57, v57
	v_log_f32_e32 v53, v50
	v_rcp_f32_e32 v42, v42
	v_cvt_pk_bf16_f32 v50, v54, v55
	v_cvt_pk_bf16_f32 v51, v56, v57
	v_cvt_pk_bf16_f32 v52, v58, v59
	v_cvt_pk_bf16_f32 v53, v60, v53
	v_lshl_add_u64 v[54:55], v[66:67], 0, vcc
	v_fma_f32 v42, v42, v122, v170
	global_store_dwordx4 v[54:55], v[50:53], off nt
	v_max_f32_e32 v46, v46, v46
	v_max_f32_e32 v47, v47, v47
	v_log_f32_e32 v52, v42
	v_max_f32_e32 v42, v43, v43
	v_med3_f32 v42, v42, s17, v162
	v_mul_f32_e32 v42, 0xbfb8aa3b, v42
	v_exp_f32_e32 v42, v42
	v_max_f32_e32 v48, v48, v48
	v_max_f32_e32 v49, v49, v49
	v_med3_f32 v46, v46, s17, v162
	v_add_f32_e32 v42, 1.0, v42
	v_rcp_f32_e32 v42, v42
	v_med3_f32 v47, v47, s17, v162
	v_med3_f32 v48, v48, s17, v162
	v_med3_f32 v49, v49, s17, v162
	v_fma_f32 v42, v42, v181, v169
	v_log_f32_e32 v53, v42
	v_max_f32_e32 v42, v44, v44
	v_med3_f32 v42, v42, s17, v162
	v_mul_f32_e32 v42, 0xbfb8aa3b, v42
	v_exp_f32_e32 v42, v42
	v_mul_f32_e32 v46, 0xbfb8aa3b, v46
	v_mul_f32_e32 v47, 0xbfb8aa3b, v47
	v_mul_f32_e32 v48, 0xbfb8aa3b, v48
	v_add_f32_e32 v42, 1.0, v42
	v_rcp_f32_e32 v42, v42
	v_mul_f32_e32 v49, 0xbfb8aa3b, v49
	v_exp_f32_e32 v46, v46
	v_exp_f32_e32 v47, v47
	v_fma_f32 v42, v42, v128, v168
	v_log_f32_e32 v54, v42
	v_max_f32_e32 v42, v45, v45
	v_med3_f32 v42, v42, s17, v162
	v_mul_f32_e32 v42, 0xbfb8aa3b, v42
	v_exp_f32_e32 v48, v48
	v_exp_f32_e32 v49, v49
	v_exp_f32_e32 v42, v42
	v_max_f32_e32 v34, v34, v34
	v_med3_f32 v34, v34, s17, v162
	v_add_f32_e32 v46, 1.0, v46
	v_add_f32_e32 v47, 1.0, v47
	v_add_f32_e32 v48, 1.0, v48
	v_add_f32_e32 v49, 1.0, v49
	v_add_f32_e32 v42, 1.0, v42
	v_mul_f32_e32 v34, 0xbfb8aa3b, v34
	v_rcp_f32_e32 v46, v46
	v_rcp_f32_e32 v47, v47
	v_rcp_f32_e32 v48, v48
	v_rcp_f32_e32 v49, v49
	v_rcp_f32_e32 v42, v42
	v_exp_f32_e32 v34, v34
	v_fma_f32 v46, v46, v133, v179
	v_fma_f32 v47, v47, v127, v175
	v_fma_f32 v48, v48, v126, v173
	v_fma_f32 v49, v49, v180, v171
	v_fma_f32 v42, v42, v125, v167
	v_add_f32_e32 v34, 1.0, v34
	v_log_f32_e32 v46, v46
	v_log_f32_e32 v47, v47
	v_log_f32_e32 v48, v48
	v_log_f32_e32 v49, v49
	v_log_f32_e32 v45, v42
	v_rcp_f32_e32 v34, v34
	v_lshl_add_u64 v[50:51], v[66:67], 0, s[8:9]
	v_cvt_pk_bf16_f32 v42, v46, v47
	v_cvt_pk_bf16_f32 v43, v48, v49
	v_cvt_pk_bf16_f32 v44, v52, v53
	v_cvt_pk_bf16_f32 v45, v54, v45
	v_fma_f32 v34, v34, v118, v177
	global_store_dwordx4 v[50:51], v[42:45], off nt
	v_max_f32_e32 v38, v38, v38
	v_max_f32_e32 v39, v39, v39
	v_log_f32_e32 v42, v34
	v_max_f32_e32 v34, v35, v35
	v_med3_f32 v34, v34, s17, v162
	v_mul_f32_e32 v34, 0xbfb8aa3b, v34
	v_exp_f32_e32 v34, v34
	v_max_f32_e32 v40, v40, v40
	v_max_f32_e32 v41, v41, v41
	v_med3_f32 v38, v38, s17, v162
	v_add_f32_e32 v34, 1.0, v34
	v_rcp_f32_e32 v34, v34
	v_med3_f32 v39, v39, s17, v162
	v_med3_f32 v40, v40, s17, v162
	v_med3_f32 v41, v41, s17, v162
	v_fma_f32 v34, v34, v129, v130
	v_log_f32_e32 v43, v34
	v_max_f32_e32 v34, v36, v36
	v_med3_f32 v34, v34, s17, v162
	v_mul_f32_e32 v34, 0xbfb8aa3b, v34
	v_exp_f32_e32 v34, v34
	v_mul_f32_e32 v38, 0xbfb8aa3b, v38
	v_mul_f32_e32 v39, 0xbfb8aa3b, v39
	v_mul_f32_e32 v40, 0xbfb8aa3b, v40
	v_add_f32_e32 v34, 1.0, v34
	v_rcp_f32_e32 v34, v34
	v_mul_f32_e32 v41, 0xbfb8aa3b, v41
	v_exp_f32_e32 v38, v38
	v_exp_f32_e32 v39, v39
	v_fma_f32 v34, v34, v120, v131
	v_log_f32_e32 v44, v34
	v_max_f32_e32 v34, v37, v37
	v_med3_f32 v34, v34, s17, v162
	v_mul_f32_e32 v34, 0xbfb8aa3b, v34
	v_exp_f32_e32 v40, v40
	v_exp_f32_e32 v41, v41
	v_exp_f32_e32 v34, v34
	v_max_f32_e32 v26, v26, v26
	v_med3_f32 v26, v26, s17, v162
	v_add_f32_e32 v38, 1.0, v38
	v_add_f32_e32 v39, 1.0, v39
	v_add_f32_e32 v40, 1.0, v40
	v_add_f32_e32 v41, 1.0, v41
	v_add_f32_e32 v34, 1.0, v34
	v_mul_f32_e32 v26, 0xbfb8aa3b, v26
	v_rcp_f32_e32 v38, v38
	v_rcp_f32_e32 v39, v39
	v_rcp_f32_e32 v40, v40
	v_rcp_f32_e32 v41, v41
	v_rcp_f32_e32 v34, v34
	v_exp_f32_e32 v26, v26
	v_fma_f32 v38, v38, v124, v178
	v_fma_f32 v39, v39, v123, v174
	v_fma_f32 v40, v40, v119, v176
	v_fma_f32 v41, v41, v121, v172
	v_fma_f32 v34, v34, v116, v132
	v_add_f32_e32 v26, 1.0, v26
	v_log_f32_e32 v38, v38
	v_log_f32_e32 v39, v39
	v_log_f32_e32 v40, v40
	v_log_f32_e32 v41, v41
	v_log_f32_e32 v37, v34
	v_rcp_f32_e32 v26, v26
	v_cvt_pk_bf16_f32 v34, v38, v39
	v_cvt_pk_bf16_f32 v35, v40, v41
	v_cvt_pk_bf16_f32 v36, v42, v43
	v_cvt_pk_bf16_f32 v37, v44, v37
	v_lshl_add_u64 v[38:39], v[50:51], 0, vcc
	v_fma_f32 v26, v26, v122, v170
	global_store_dwordx4 v[38:39], v[34:37], off nt
	v_max_f32_e32 v30, v30, v30
	v_max_f32_e32 v31, v31, v31
	v_log_f32_e32 v36, v26
	v_max_f32_e32 v26, v27, v27
	v_med3_f32 v26, v26, s17, v162
	v_mul_f32_e32 v26, 0xbfb8aa3b, v26
; __device__ __forceinline__ unsigned cvt_pk_bf16_c(float lo, float hi) { f32x2c v = {lo, hi}; bf16x2c b = __builtin_convertvector(v, bf16x2c); return __builtin_bit_cast(unsigned, b); }
;     __device__ __forceinline__ void operator()(const f32x4 (&acc)[2][2][4][2], const Unit& u, int wr, int wc, int fr, int fq) const {
;     ...
;                     for (int bj = 0; bj < 2; ++bj) { float o[8];
; #pragma unroll
;                         for (int e = 0; e < 8; ++e) { const float v = fminf(fmaxf(acc[ai][bj][m][e >> 2][e & 3], -30.f), 30.f); const float sg = __builtin_amdgcn_rcpf(1.0f + __expf(-v)); o[e] = __log2f(lb[bj][e] + (1.0f - lb[bj][e]) * sg); }
;                         u32x4 w; w.x = cvt_pk_bf16_c(o[0], o[1]); w.y = cvt_pk_bf16_c(o[2], o[3]); w.z = cvt_pk_bf16_c(o[4], o[5]); w.w = cvt_pk_bf16_c(o[6], o[7]);
;                         *(u32x4*)(rowp + bj * bjstride) = w; } }
	v_exp_f32_e32 v26, v26
	v_max_f32_e32 v32, v32, v32
	v_max_f32_e32 v33, v33, v33
	v_med3_f32 v30, v30, s17, v162
	v_add_f32_e32 v26, 1.0, v26
	v_rcp_f32_e32 v26, v26
	v_med3_f32 v31, v31, s17, v162
	v_med3_f32 v32, v32, s17, v162
	v_med3_f32 v33, v33, s17, v162
	v_fma_f32 v26, v26, v181, v169
	v_log_f32_e32 v37, v26
	v_max_f32_e32 v26, v28, v28
	v_med3_f32 v26, v26, s17, v162
	v_mul_f32_e32 v26, 0xbfb8aa3b, v26
	v_exp_f32_e32 v26, v26
	v_mul_f32_e32 v30, 0xbfb8aa3b, v30
	v_mul_f32_e32 v31, 0xbfb8aa3b, v31
	v_mul_f32_e32 v32, 0xbfb8aa3b, v32
	v_add_f32_e32 v26, 1.0, v26
	v_rcp_f32_e32 v26, v26
	v_mul_f32_e32 v33, 0xbfb8aa3b, v33
	v_exp_f32_e32 v30, v30
	v_exp_f32_e32 v31, v31
	v_fma_f32 v26, v26, v128, v168
	v_log_f32_e32 v38, v26
	v_max_f32_e32 v26, v29, v29
	v_med3_f32 v26, v26, s17, v162
	v_mul_f32_e32 v26, 0xbfb8aa3b, v26
	v_exp_f32_e32 v32, v32
	v_exp_f32_e32 v33, v33
	v_exp_f32_e32 v26, v26
	v_max_f32_e32 v18, v18, v18
	v_med3_f32 v18, v18, s17, v162
	v_add_f32_e32 v30, 1.0, v30
	v_add_f32_e32 v31, 1.0, v31
	v_add_f32_e32 v32, 1.0, v32
	v_add_f32_e32 v33, 1.0, v33
	v_add_f32_e32 v26, 1.0, v26
	v_mul_f32_e32 v18, 0xbfb8aa3b, v18
	v_rcp_f32_e32 v30, v30
	v_rcp_f32_e32 v31, v31
	v_rcp_f32_e32 v32, v32
	v_rcp_f32_e32 v33, v33
	v_rcp_f32_e32 v26, v26
	v_exp_f32_e32 v18, v18
	v_fma_f32 v30, v30, v133, v179
	v_fma_f32 v31, v31, v127, v175
	v_fma_f32 v32, v32, v126, v173
	v_fma_f32 v33, v33, v180, v171
	v_fma_f32 v26, v26, v125, v167
	v_add_f32_e32 v18, 1.0, v18
	v_log_f32_e32 v30, v30
	v_log_f32_e32 v31, v31
	v_log_f32_e32 v32, v32
	v_log_f32_e32 v33, v33
	v_log_f32_e32 v29, v26
	v_rcp_f32_e32 v18, v18
	v_max_f32_e32 v10, v10, v10
	v_med3_f32 v10, v10, s17, v162
	v_mul_f32_e32 v10, 0xbfb8aa3b, v10
	v_exp_f32_e32 v10, v10
	v_lshl_add_u64 v[34:35], v[50:51], 0, s[8:9]
	v_cvt_pk_bf16_f32 v26, v30, v31
	v_cvt_pk_bf16_f32 v27, v32, v33
	v_cvt_pk_bf16_f32 v28, v36, v37
	v_cvt_pk_bf16_f32 v29, v38, v29
	v_fma_f32 v18, v18, v118, v177
	global_store_dwordx4 v[34:35], v[26:29], off nt
	v_add_f32_e32 v10, 1.0, v10
	v_rcp_f32_e32 v10, v10
	v_log_f32_e32 v26, v18
	v_max_f32_e32 v18, v19, v19
	v_med3_f32 v18, v18, s17, v162
	v_mul_f32_e32 v18, 0xbfb8aa3b, v18
	v_exp_f32_e32 v18, v18
	v_fmac_f32_e32 v170, v10, v122
	v_max_f32_e32 v10, v11, v11
	v_med3_f32 v10, v10, s17, v162
	v_add_f32_e32 v18, 1.0, v18
	v_rcp_f32_e32 v18, v18
	v_mul_f32_e32 v10, 0xbfb8aa3b, v10
	v_exp_f32_e32 v10, v10
	v_max_f32_e32 v22, v22, v22
	v_fma_f32 v18, v18, v129, v130
	v_log_f32_e32 v27, v18
	v_max_f32_e32 v18, v20, v20
	v_med3_f32 v18, v18, s17, v162
	v_add_f32_e32 v10, 1.0, v10
	v_mul_f32_e32 v18, 0xbfb8aa3b, v18
	v_rcp_f32_e32 v10, v10
	v_exp_f32_e32 v18, v18
	v_max_f32_e32 v23, v23, v23
	v_max_f32_e32 v24, v24, v24
	v_fmac_f32_e32 v169, v10, v181
	v_max_f32_e32 v10, v12, v12
	v_add_f32_e32 v18, 1.0, v18
	v_med3_f32 v10, v10, s17, v162
	v_rcp_f32_e32 v18, v18
	v_mul_f32_e32 v10, 0xbfb8aa3b, v10
	v_exp_f32_e32 v10, v10
	v_max_f32_e32 v25, v25, v25
	v_fma_f32 v18, v18, v120, v131
	v_log_f32_e32 v28, v18
	v_max_f32_e32 v18, v21, v21
	v_add_f32_e32 v10, 1.0, v10
	v_med3_f32 v22, v22, s17, v162
	v_med3_f32 v23, v23, s17, v162
	v_med3_f32 v24, v24, s17, v162
	v_med3_f32 v25, v25, s17, v162
	v_med3_f32 v18, v18, s17, v162
	v_rcp_f32_e32 v10, v10
	v_mul_f32_e32 v22, 0xbfb8aa3b, v22
	v_mul_f32_e32 v23, 0xbfb8aa3b, v23
	v_mul_f32_e32 v24, 0xbfb8aa3b, v24
	v_mul_f32_e32 v25, 0xbfb8aa3b, v25
	v_mul_f32_e32 v18, 0xbfb8aa3b, v18
	v_exp_f32_e32 v22, v22
	v_exp_f32_e32 v23, v23
	v_exp_f32_e32 v24, v24
	v_exp_f32_e32 v25, v25
	v_exp_f32_e32 v18, v18
	v_max_f32_e32 v14, v14, v14
	v_max_f32_e32 v15, v15, v15
	v_max_f32_e32 v16, v16, v16
	v_max_f32_e32 v17, v17, v17
	v_fmac_f32_e32 v168, v10, v128
	v_max_f32_e32 v10, v13, v13
	v_max_f32_e32 v6, v6, v6
	v_max_f32_e32 v7, v7, v7
	v_max_f32_e32 v8, v8, v8
	v_max_f32_e32 v9, v9, v9
	v_max_f32_e32 v2, v2, v2
	v_max_f32_e32 v3, v3, v3
	v_max_f32_e32 v4, v4, v4
	v_max_f32_e32 v5, v5, v5
	v_med3_f32 v14, v14, s17, v162
	v_med3_f32 v15, v15, s17, v162
; __device__ __forceinline__ unsigned cvt_pk_bf16_c(float lo, float hi) { f32x2c v = {lo, hi}; bf16x2c b = __builtin_convertvector(v, bf16x2c); return __builtin_bit_cast(unsigned, b); }
;     __device__ __forceinline__ void operator()(const f32x4 (&acc)[2][2][4][2], const Unit& u, int wr, int wc, int fr, int fq) const {
;     ...
;                     for (int bj = 0; bj < 2; ++bj) { float o[8];
; #pragma unroll
;                         for (int e = 0; e < 8; ++e) { const float v = fminf(fmaxf(acc[ai][bj][m][e >> 2][e & 3], -30.f), 30.f); const float sg = __builtin_amdgcn_rcpf(1.0f + __expf(-v)); o[e] = __log2f(lb[bj][e] + (1.0f - lb[bj][e]) * sg); }
;                         u32x4 w; w.x = cvt_pk_bf16_c(o[0], o[1]); w.y = cvt_pk_bf16_c(o[2], o[3]); w.z = cvt_pk_bf16_c(o[4], o[5]); w.w = cvt_pk_bf16_c(o[6], o[7]);
;                         *(u32x4*)(rowp + bj * bjstride) = w; } }
;     ...
;                     *(u32x4*)(rowp + bj * bjstride) = w; } }
	v_med3_f32 v16, v16, s17, v162
	v_med3_f32 v17, v17, s17, v162
	v_med3_f32 v10, v10, s17, v162
	v_med3_f32 v6, v6, s17, v162
	v_med3_f32 v7, v7, s17, v162
	v_med3_f32 v8, v8, s17, v162
	v_med3_f32 v9, v9, s17, v162
	v_med3_f32 v2, v2, s17, v162
	v_med3_f32 v3, v3, s17, v162
	v_med3_f32 v4, v4, s17, v162
	v_med3_f32 v5, v5, s17, v162
	v_add_f32_e32 v22, 1.0, v22
	v_add_f32_e32 v23, 1.0, v23
	v_add_f32_e32 v24, 1.0, v24
	v_add_f32_e32 v25, 1.0, v25
	v_add_f32_e32 v18, 1.0, v18
	v_mul_f32_e32 v14, 0xbfb8aa3b, v14
	v_mul_f32_e32 v15, 0xbfb8aa3b, v15
	v_mul_f32_e32 v16, 0xbfb8aa3b, v16
	v_mul_f32_e32 v17, 0xbfb8aa3b, v17
	v_mul_f32_e32 v10, 0xbfb8aa3b, v10
	v_mul_f32_e32 v6, 0xbfb8aa3b, v6
	v_mul_f32_e32 v7, 0xbfb8aa3b, v7
	v_mul_f32_e32 v8, 0xbfb8aa3b, v8
	v_mul_f32_e32 v9, 0xbfb8aa3b, v9
	v_mul_f32_e32 v2, 0xbfb8aa3b, v2
	v_mul_f32_e32 v3, 0xbfb8aa3b, v3
	v_mul_f32_e32 v4, 0xbfb8aa3b, v4
	v_mul_f32_e32 v5, 0xbfb8aa3b, v5
	v_rcp_f32_e32 v22, v22
	v_rcp_f32_e32 v23, v23
	v_rcp_f32_e32 v24, v24
	v_rcp_f32_e32 v25, v25
	v_rcp_f32_e32 v18, v18
	v_exp_f32_e32 v14, v14
	v_exp_f32_e32 v15, v15
	v_exp_f32_e32 v16, v16
	v_exp_f32_e32 v17, v17
	v_exp_f32_e32 v10, v10
	v_exp_f32_e32 v6, v6
	v_exp_f32_e32 v7, v7
	v_exp_f32_e32 v8, v8
	v_exp_f32_e32 v9, v9
	v_exp_f32_e32 v2, v2
	v_exp_f32_e32 v3, v3
	v_exp_f32_e32 v4, v4
	v_exp_f32_e32 v5, v5
	v_fma_f32 v22, v22, v124, v178
	v_fma_f32 v23, v23, v123, v174
	v_fma_f32 v24, v24, v119, v176
	v_fma_f32 v25, v25, v121, v172
	v_fma_f32 v18, v18, v116, v132
	v_add_f32_e32 v14, 1.0, v14
	v_add_f32_e32 v15, 1.0, v15
	v_add_f32_e32 v16, 1.0, v16
	v_add_f32_e32 v17, 1.0, v17
	v_add_f32_e32 v10, 1.0, v10
	v_add_f32_e32 v6, 1.0, v6
	v_add_f32_e32 v7, 1.0, v7
	v_add_f32_e32 v8, 1.0, v8
	v_add_f32_e32 v9, 1.0, v9
	v_add_f32_e32 v2, 1.0, v2
	v_add_f32_e32 v3, 1.0, v3
	v_add_f32_e32 v4, 1.0, v4
	v_add_f32_e32 v5, 1.0, v5
	v_log_f32_e32 v22, v22
	v_log_f32_e32 v23, v23
	v_log_f32_e32 v24, v24
	v_log_f32_e32 v25, v25
	v_log_f32_e32 v21, v18
	v_rcp_f32_e32 v14, v14
	v_rcp_f32_e32 v15, v15
	v_rcp_f32_e32 v16, v16
	v_rcp_f32_e32 v17, v17
	v_rcp_f32_e32 v10, v10
	v_rcp_f32_e32 v6, v6
	v_rcp_f32_e32 v7, v7
	v_rcp_f32_e32 v8, v8
	v_rcp_f32_e32 v9, v9
	v_rcp_f32_e32 v2, v2
	v_rcp_f32_e32 v3, v3
	v_rcp_f32_e32 v4, v4
	v_rcp_f32_e32 v5, v5
	v_cvt_pk_bf16_f32 v18, v22, v23
	v_cvt_pk_bf16_f32 v19, v24, v25
	v_cvt_pk_bf16_f32 v20, v26, v27
	v_cvt_pk_bf16_f32 v21, v28, v21
	v_lshl_add_u64 v[22:23], v[34:35], 0, vcc
	v_fmac_f32_e32 v179, v14, v133
	v_fmac_f32_e32 v175, v15, v127
	v_fmac_f32_e32 v173, v16, v126
	v_fmac_f32_e32 v171, v17, v180
	v_fmac_f32_e32 v167, v10, v125
	v_fmac_f32_e32 v178, v6, v124
	v_fmac_f32_e32 v174, v7, v123
	v_fmac_f32_e32 v176, v8, v119
	v_fmac_f32_e32 v172, v9, v121
	v_fmac_f32_e32 v177, v2, v118
	v_fmac_f32_e32 v130, v3, v129
	v_fmac_f32_e32 v131, v4, v120
	v_fmac_f32_e32 v132, v5, v116
	global_store_dwordx4 v[22:23], v[18:21], off nt
	v_log_f32_e32 v14, v179
	v_log_f32_e32 v15, v175
	v_log_f32_e32 v16, v173
	v_log_f32_e32 v17, v171
	v_log_f32_e32 v20, v170
	v_log_f32_e32 v21, v169
	v_log_f32_e32 v22, v168
	v_log_f32_e32 v13, v167
	v_log_f32_e32 v6, v178
	v_log_f32_e32 v7, v174
	v_log_f32_e32 v8, v176
	v_log_f32_e32 v9, v172
	v_log_f32_e32 v2, v177
	v_log_f32_e32 v3, v130
	v_log_f32_e32 v4, v131
	v_log_f32_e32 v5, v132
	s_add_i32 s97, s91, s87
	v_lshl_add_u64 v[18:19], v[34:35], 0, s[8:9]
	v_cvt_pk_bf16_f32 v10, v14, v15
	v_cvt_pk_bf16_f32 v11, v16, v17
	v_cvt_pk_bf16_f32 v12, v20, v21
	v_cvt_pk_bf16_f32 v13, v22, v13
	v_cvt_pk_bf16_f32 v130, v6, v7
	v_cvt_pk_bf16_f32 v131, v8, v9
	v_cvt_pk_bf16_f32 v132, v2, v3
	v_cvt_pk_bf16_f32 v133, v4, v5
	global_store_dwordx4 v[18:19], v[10:13], off nt
.LBB0_324:
	v_lshl_add_u64 v[2:3], v[156:157], 0, s[96:97]
	v_lshl_add_u64 v[2:3], s[84:85], 1, v[2:3]
	s_andn2_b64 vcc, exec, s[0:1]
	s_mov_b64 s[0:1], -1
	global_store_dwordx4 v[2:3], v[130:133], off nt
	s_cbranch_vccnz .LBB0_305
	s_andn2_b64 vcc, exec, s[56:57]
	s_cbranch_vccnz .LBB0_304
	s_barrier
	s_branch .LBB0_304

; __device__ __forceinline__ unsigned cvt_pk_bf16(float lo, float hi) { unsigned r; asm volatile("v_cvt_pk_bf16_f32 %0, %1, %2" : "=v"(r) : "v"(lo), "v"(hi)); return r; }
;     __device__ __forceinline__ void operator()(const f32x4 (&acc)[2][2][4][2], const Unit& u, int wr, int wc, int fr, int fq) const {
;         const int row0 = u.pm * BM + wr * 64 + fr; const int colt = u.pn * BM;
;         bf16_t* p0; size_t rstride, bjstride;
;         if (mode == 1) { rstride = 32; p0 = O + ((size_t)(colt / 32 + wc) * ldc + row0) * 32 + 8 * fq; bjstride = (size_t)4 * ldc * 32; }
;         else if (colt >= hm_lo && colt < hm_hi) { rstride = 64; p0 = HM + ((size_t)((colt - hm_lo) / 64 + (wc >> 1)) * hm_rows + row0) * 64 + (wc & 1) * 32 + 8 * fq; bjstride = (size_t)2 * hm_rows * 64; }
;         else { rstride = ldc; p0 = O + (size_t)row0 * ldc + (colt - (colt >= hm_hi ? hm_hi - hm_lo : 0)) + wc * 32 + 8 * fq; bjstride = HALF; }
;     ...
; #pragma unroll
;         for (int ai = 0; ai < 2; ++ai)
; #pragma unroll
;             for (int m = 0; m < 4; ++m) { bf16_t* rowp = p0 + (size_t)(ai * HALF + m * 16) * rstride;
; #pragma unroll
;                 for (int bj = 0; bj < 2; ++bj) { const f32x4 v0 = acc[ai][bj][m][0], v1 = acc[ai][bj][m][1];
;                     u32x4 w; w.x = cvt_pk_bf16(v0[0], v0[1]); w.y = cvt_pk_bf16(v0[2], v0[3]); w.z = cvt_pk_bf16(v1[0], v1[1]); w.w = cvt_pk_bf16(v1[2], v1[3]);
;                     *(u32x4*)(rowp + bj * bjstride) = w; } }
.LBB0_595:
	v_lshl_add_u32 v148, s42, 8, v150
	v_ashrrev_i32_e32 v149, 31, v148
	s_lshl_b32 s44, s31, 8
	v_lshlrev_b64 v[148:149], 14, v[148:149]
	v_lshl_add_u64 v[148:149], s[24:25], 0, v[148:149]
	s_ashr_i32 s45, s44, 31
	v_lshl_add_u64 v[148:149], s[44:45], 1, v[148:149]
	s_mov_b32 s31, s9
	v_lshl_add_u64 v[148:149], v[148:149], 0, s[30:31]
	v_lshl_add_u64 v[148:149], v[148:149], 0, v[138:139]
	s_mov_b32 s31, 0x40000
	v_cvt_pk_bf16_f32 v126, v126, v127
	v_cvt_pk_bf16_f32 v127, v128, v129
	v_cvt_pk_bf16_f32 v128, v122, v123
	v_cvt_pk_bf16_f32 v129, v124, v125
	global_store_dwordx4 v[148:149], v[126:129], off nt
	v_cvt_pk_bf16_f32 v114, v114, v115
	v_cvt_pk_bf16_f32 v115, v116, v117
	v_cvt_pk_bf16_f32 v116, v106, v107
	v_cvt_pk_bf16_f32 v117, v108, v109
	global_store_dwordx4 v[148:149], v[114:117], off offset:256 nt
	v_cvt_pk_bf16_f32 v106, v118, v119
	v_cvt_pk_bf16_f32 v107, v120, v121
	v_cvt_pk_bf16_f32 v108, v110, v111
	v_add_co_u32_e32 v110, vcc, s31, v148
	s_mov_b32 s31, 0x80000
	s_nop 0
	v_addc_co_u32_e32 v111, vcc, 0, v149, vcc
	v_cvt_pk_bf16_f32 v109, v112, v113
	global_store_dwordx4 v[110:111], v[106:109], off nt
	v_cvt_pk_bf16_f32 v98, v98, v99
	v_cvt_pk_bf16_f32 v99, v100, v101
	v_cvt_pk_bf16_f32 v100, v90, v91
	v_cvt_pk_bf16_f32 v101, v92, v93
	global_store_dwordx4 v[110:111], v[98:101], off offset:256 nt
	v_cvt_pk_bf16_f32 v90, v102, v103
	v_cvt_pk_bf16_f32 v91, v104, v105
	v_cvt_pk_bf16_f32 v92, v94, v95
	v_add_co_u32_e32 v94, vcc, s31, v148
	s_mov_b32 s31, 0xc0000
	s_nop 0
	v_addc_co_u32_e32 v95, vcc, 0, v149, vcc
	v_cvt_pk_bf16_f32 v93, v96, v97
	global_store_dwordx4 v[94:95], v[90:93], off nt
	v_cvt_pk_bf16_f32 v82, v82, v83
	v_cvt_pk_bf16_f32 v83, v84, v85
	v_cvt_pk_bf16_f32 v84, v74, v75
	v_cvt_pk_bf16_f32 v85, v76, v77
	global_store_dwordx4 v[94:95], v[82:85], off offset:256 nt
	v_cvt_pk_bf16_f32 v74, v86, v87
	v_cvt_pk_bf16_f32 v75, v88, v89
	v_cvt_pk_bf16_f32 v76, v78, v79
	v_add_co_u32_e32 v78, vcc, s31, v148
	s_mov_b32 s31, 0x200000
	s_nop 0
	v_addc_co_u32_e32 v79, vcc, 0, v149, vcc
	v_cvt_pk_bf16_f32 v77, v80, v81
	global_store_dwordx4 v[78:79], v[74:77], off nt
	v_cvt_pk_bf16_f32 v70, v70, v71
	v_cvt_pk_bf16_f32 v71, v72, v73
	v_cvt_pk_bf16_f32 v72, v66, v67
	v_cvt_pk_bf16_f32 v73, v68, v69
	global_store_dwordx4 v[78:79], v[70:73], off offset:256 nt
	v_cvt_pk_bf16_f32 v62, v62, v63
	v_cvt_pk_bf16_f32 v63, v64, v65
	v_cvt_pk_bf16_f32 v64, v58, v59
	v_add_co_u32_e32 v58, vcc, s31, v148
	s_mov_b32 s31, 0x240000
	s_nop 0
	v_addc_co_u32_e32 v59, vcc, 0, v149, vcc
	v_cvt_pk_bf16_f32 v65, v60, v61
	global_store_dwordx4 v[58:59], v[62:65], off nt
	v_cvt_pk_bf16_f32 v50, v50, v51
	v_cvt_pk_bf16_f32 v51, v52, v53
	v_cvt_pk_bf16_f32 v52, v42, v43
	v_cvt_pk_bf16_f32 v53, v44, v45
	global_store_dwordx4 v[58:59], v[50:53], off offset:256 nt
	v_cvt_pk_bf16_f32 v42, v54, v55
	v_cvt_pk_bf16_f32 v43, v56, v57
	v_cvt_pk_bf16_f32 v44, v46, v47
	v_add_co_u32_e32 v46, vcc, s31, v148
	s_mov_b32 s31, 0x280000
	s_nop 0
	v_addc_co_u32_e32 v47, vcc, 0, v149, vcc
	v_cvt_pk_bf16_f32 v45, v48, v49
	global_store_dwordx4 v[46:47], v[42:45], off nt
	v_cvt_pk_bf16_f32 v34, v34, v35
	v_cvt_pk_bf16_f32 v35, v36, v37
	v_cvt_pk_bf16_f32 v36, v26, v27
	v_cvt_pk_bf16_f32 v37, v28, v29
	global_store_dwordx4 v[46:47], v[34:37], off offset:256 nt
	v_cvt_pk_bf16_f32 v26, v38, v39
	v_cvt_pk_bf16_f32 v27, v40, v41
	v_cvt_pk_bf16_f32 v28, v30, v31
	v_add_co_u32_e32 v30, vcc, s31, v148
	s_mov_b32 s31, 0x2c0000
	s_nop 0
	v_addc_co_u32_e32 v31, vcc, 0, v149, vcc
	v_cvt_pk_bf16_f32 v29, v32, v33
	global_store_dwordx4 v[30:31], v[26:29], off nt
	v_cvt_pk_bf16_f32 v18, v18, v19
	v_cvt_pk_bf16_f32 v19, v20, v21
	v_cvt_pk_bf16_f32 v20, v10, v11
	v_cvt_pk_bf16_f32 v21, v12, v13
	global_store_dwordx4 v[30:31], v[18:21], off offset:256 nt
	v_cvt_pk_bf16_f32 v10, v22, v23
	v_cvt_pk_bf16_f32 v11, v24, v25
	v_cvt_pk_bf16_f32 v12, v14, v15
	v_add_co_u32_e32 v14, vcc, s31, v148
	v_cvt_pk_bf16_f32 v13, v16, v17
	s_nop 1
	v_addc_co_u32_e32 v15, vcc, 0, v149, vcc
	s_andn2_b64 vcc, exec, s[0:1]
	s_mov_b64 s[0:1], -1
	global_store_dwordx4 v[14:15], v[10:13], off nt
	v_cvt_pk_bf16_f32 v6, v6, v7
	v_cvt_pk_bf16_f32 v7, v8, v9
	v_cvt_pk_bf16_f32 v8, v2, v3
	v_cvt_pk_bf16_f32 v9, v4, v5
	global_store_dwordx4 v[14:15], v[6:9], off offset:256 nt
	s_cbranch_vccnz .LBB0_584
	s_andn2_b64 vcc, exec, s[22:23]
	s_cbranch_vccnz .LBB0_583
	s_barrier
	s_branch .LBB0_583

; __device__ __forceinline__ unsigned cvt_pk_bf16(float lo, float hi) { unsigned r; asm volatile("v_cvt_pk_bf16_f32 %0, %1, %2" : "=v"(r) : "v"(lo), "v"(hi)); return r; }
;     __device__ __forceinline__ void operator()(const f32x4 (&acc)[2][2][4][2], const Unit& u, int wr, int wc, int fr, int fq) const {
;         const int row0 = u.pm * BM + wr * 64 + fr; const int colt = u.pn * BM;
;         bf16_t* p0; size_t rstride, bjstride;
;         if (mode == 1) { rstride = 32; p0 = O + ((size_t)(colt / 32 + wc) * ldc + row0) * 32 + 8 * fq; bjstride = (size_t)4 * ldc * 32; }
;         else if (colt >= hm_lo && colt < hm_hi) { rstride = 64; p0 = HM + ((size_t)((colt - hm_lo) / 64 + (wc >> 1)) * hm_rows + row0) * 64 + (wc & 1) * 32 + 8 * fq; bjstride = (size_t)2 * hm_rows * 64; }
;         else { rstride = ldc; p0 = O + (size_t)row0 * ldc + (colt - (colt >= hm_hi ? hm_hi - hm_lo : 0)) + wc * 32 + 8 * fq; bjstride = HALF; }
;     ...
; #pragma unroll
;         for (int ai = 0; ai < 2; ++ai)
; #pragma unroll
;             for (int m = 0; m < 4; ++m) { bf16_t* rowp = p0 + (size_t)(ai * HALF + m * 16) * rstride;
; #pragma unroll
;                 for (int bj = 0; bj < 2; ++bj) { const f32x4 v0 = acc[ai][bj][m][0], v1 = acc[ai][bj][m][1];
;                     u32x4 w; w.x = cvt_pk_bf16(v0[0], v0[1]); w.y = cvt_pk_bf16(v0[2], v0[3]); w.z = cvt_pk_bf16(v1[0], v1[1]); w.w = cvt_pk_bf16(v1[2], v1[3]);
;                     *(u32x4*)(rowp + bj * bjstride) = w; } }
.LBB0_653:
	v_lshl_add_u32 v146, s40, 8, v148
	v_ashrrev_i32_e32 v147, 31, v146
	s_lshl_b32 s42, s54, 8
	v_lshlrev_b64 v[146:147], 14, v[146:147]
	v_lshl_add_u64 v[146:147], s[24:25], 0, v[146:147]
	s_ashr_i32 s43, s42, 31
	v_lshl_add_u64 v[146:147], s[42:43], 1, v[146:147]
	v_lshl_add_u64 v[146:147], v[146:147], 0, s[8:9]
	v_lshl_add_u64 v[146:147], v[146:147], 0, v[138:139]
	s_mov_b32 s31, 0x40000
	v_cvt_pk_bf16_f32 v126, v126, v127
	v_cvt_pk_bf16_f32 v127, v128, v129
	v_cvt_pk_bf16_f32 v128, v122, v123
	v_cvt_pk_bf16_f32 v129, v124, v125
	global_store_dwordx4 v[146:147], v[126:129], off nt
	v_cvt_pk_bf16_f32 v114, v114, v115
	v_cvt_pk_bf16_f32 v115, v116, v117
	v_cvt_pk_bf16_f32 v116, v106, v107
	v_cvt_pk_bf16_f32 v117, v108, v109
	global_store_dwordx4 v[146:147], v[114:117], off offset:256 nt
	v_cvt_pk_bf16_f32 v106, v118, v119
	v_cvt_pk_bf16_f32 v107, v120, v121
	v_cvt_pk_bf16_f32 v108, v110, v111
	v_add_co_u32_e32 v110, vcc, s31, v146
	s_mov_b32 s31, 0x80000
	s_nop 0
	v_addc_co_u32_e32 v111, vcc, 0, v147, vcc
	v_cvt_pk_bf16_f32 v109, v112, v113
	global_store_dwordx4 v[110:111], v[106:109], off nt
	v_cvt_pk_bf16_f32 v98, v98, v99
	v_cvt_pk_bf16_f32 v99, v100, v101
	v_cvt_pk_bf16_f32 v100, v90, v91
	v_cvt_pk_bf16_f32 v101, v92, v93
	global_store_dwordx4 v[110:111], v[98:101], off offset:256 nt
	v_cvt_pk_bf16_f32 v90, v102, v103
	v_cvt_pk_bf16_f32 v91, v104, v105
	v_cvt_pk_bf16_f32 v92, v94, v95
	v_add_co_u32_e32 v94, vcc, s31, v146
	s_mov_b32 s31, 0xc0000
	s_nop 0
	v_addc_co_u32_e32 v95, vcc, 0, v147, vcc
	v_cvt_pk_bf16_f32 v93, v96, v97
	global_store_dwordx4 v[94:95], v[90:93], off nt
	v_cvt_pk_bf16_f32 v82, v82, v83
	v_cvt_pk_bf16_f32 v83, v84, v85
	v_cvt_pk_bf16_f32 v84, v74, v75
	v_cvt_pk_bf16_f32 v85, v76, v77
	global_store_dwordx4 v[94:95], v[82:85], off offset:256 nt
	v_cvt_pk_bf16_f32 v74, v86, v87
	v_cvt_pk_bf16_f32 v75, v88, v89
	v_cvt_pk_bf16_f32 v76, v78, v79
	v_add_co_u32_e32 v78, vcc, s31, v146
	s_mov_b32 s31, 0x200000
	s_nop 0
	v_addc_co_u32_e32 v79, vcc, 0, v147, vcc
	v_cvt_pk_bf16_f32 v77, v80, v81
	global_store_dwordx4 v[78:79], v[74:77], off nt
	v_cvt_pk_bf16_f32 v70, v70, v71
	v_cvt_pk_bf16_f32 v71, v72, v73
	v_cvt_pk_bf16_f32 v72, v66, v67
	v_cvt_pk_bf16_f32 v73, v68, v69
	global_store_dwordx4 v[78:79], v[70:73], off offset:256 nt
	v_cvt_pk_bf16_f32 v62, v62, v63
	v_cvt_pk_bf16_f32 v63, v64, v65
	v_cvt_pk_bf16_f32 v64, v58, v59
	v_add_co_u32_e32 v58, vcc, s31, v146
	v_cvt_pk_bf16_f32 v65, v60, v61
	s_nop 1
	v_addc_co_u32_e32 v59, vcc, 0, v147, vcc
	global_store_dwordx4 v[58:59], v[62:65], off nt
	v_cvt_pk_bf16_f32 v50, v50, v51
	v_cvt_pk_bf16_f32 v51, v52, v53
	v_cvt_pk_bf16_f32 v52, v42, v43
	v_cvt_pk_bf16_f32 v53, v44, v45
	global_store_dwordx4 v[58:59], v[50:53], off offset:256 nt
	v_cvt_pk_bf16_f32 v42, v54, v55
	v_cvt_pk_bf16_f32 v43, v56, v57
	v_cvt_pk_bf16_f32 v44, v46, v47
	v_add_co_u32_e32 v46, vcc, s50, v146
	v_cvt_pk_bf16_f32 v45, v48, v49
	s_nop 1
	v_addc_co_u32_e32 v47, vcc, 0, v147, vcc
	global_store_dwordx4 v[46:47], v[42:45], off nt
	v_cvt_pk_bf16_f32 v34, v34, v35
	v_cvt_pk_bf16_f32 v35, v36, v37
	v_cvt_pk_bf16_f32 v36, v26, v27
	v_cvt_pk_bf16_f32 v37, v28, v29
	global_store_dwordx4 v[46:47], v[34:37], off offset:256 nt
	v_cvt_pk_bf16_f32 v26, v38, v39
	v_cvt_pk_bf16_f32 v27, v40, v41
	v_cvt_pk_bf16_f32 v28, v30, v31
	v_add_co_u32_e32 v30, vcc, s51, v146
	v_cvt_pk_bf16_f32 v29, v32, v33
	s_nop 1
	v_addc_co_u32_e32 v31, vcc, 0, v147, vcc
	global_store_dwordx4 v[30:31], v[26:29], off nt
	v_cvt_pk_bf16_f32 v18, v18, v19
	v_cvt_pk_bf16_f32 v19, v20, v21
	v_cvt_pk_bf16_f32 v20, v10, v11
	v_cvt_pk_bf16_f32 v21, v12, v13
	global_store_dwordx4 v[30:31], v[18:21], off offset:256 nt
	v_cvt_pk_bf16_f32 v10, v22, v23
	v_cvt_pk_bf16_f32 v11, v24, v25
	v_cvt_pk_bf16_f32 v12, v14, v15
	v_add_co_u32_e32 v14, vcc, s52, v146
	v_cvt_pk_bf16_f32 v13, v16, v17
	s_nop 1
	v_addc_co_u32_e32 v15, vcc, 0, v147, vcc
	s_andn2_b64 vcc, exec, s[0:1]
	s_mov_b64 s[0:1], -1
	global_store_dwordx4 v[14:15], v[10:13], off nt
	v_cvt_pk_bf16_f32 v6, v6, v7
	v_cvt_pk_bf16_f32 v7, v8, v9
	v_cvt_pk_bf16_f32 v8, v2, v3
	v_cvt_pk_bf16_f32 v9, v4, v5
	global_store_dwordx4 v[14:15], v[6:9], off offset:256 nt
	s_cbranch_vccnz .LBB0_642
	s_andn2_b64 vcc, exec, s[22:23]
	s_cbranch_vccnz .LBB0_641
	s_barrier
	s_branch .LBB0_641

; __device__ __forceinline__ unsigned cvt_pk_bf16(float lo, float hi) { unsigned r; asm volatile("v_cvt_pk_bf16_f32 %0, %1, %2" : "=v"(r) : "v"(lo), "v"(hi)); return r; }
; __device__ __forceinline__ float sigm(float x) { return __builtin_amdgcn_rcpf(1.0f + __expf(-x)); }
;     __device__ __forceinline__ void operator()(const f32x4 (&acc)[2][2][4][2], const Unit& u, int wr, int wc, int fr, int fq) const {
;     ...
;             for (int m = 0; m < 4; ++m) { bf16_t* rowp = H + (size_t)(row0 + ai * HALF + m * 16) * ldc + col0;
;                 float o[8];
; #pragma unroll
;                 for (int n = 0; n < 2; ++n)
; #pragma unroll
;                     for (int i = 0; i < 4; ++i) { const float a = acc[ai][0][m][n][i], g = acc[ai][1][m][n][i]; o[4 * n + i] = a * sigm(a) * g; }
;                 u32x4 w; w.x = cvt_pk_bf16(o[0], o[1]); w.y = cvt_pk_bf16(o[2], o[3]); w.z = cvt_pk_bf16(o[4], o[5]); w.w = cvt_pk_bf16(o[6], o[7]);
;                 *(u32x4*)rowp = w; }
.LBB0_1101:
	v_mul_f32_e32 v146, 0xbfb8aa3b, v126
	v_exp_f32_e32 v155, v146
	v_mul_f32_e32 v146, 0xbfb8aa3b, v127
	v_exp_f32_e32 v158, v146
	v_lshl_or_b32 v156, s48, 7, v150
	v_add_f32_e32 v155, 1.0, v155
	v_rcp_f32_e32 v155, v155
	v_add_f32_e32 v158, 1.0, v158
	v_rcp_f32_e32 v160, v158
	v_lshl_add_u32 v154, s26, 8, v148
	v_mul_f32_e32 v126, v126, v155
	v_mul_f32_e32 v118, v126, v118
	v_mul_f32_e32 v126, v127, v160
	v_mul_f32_e32 v127, 0xbfb8aa3b, v128
	v_exp_f32_e32 v127, v127
	v_mul_f32_e32 v155, 0xbfb8aa3b, v129
	v_exp_f32_e32 v155, v155
	v_mul_f32_e32 v119, v126, v119
	v_add_f32_e32 v126, 1.0, v127
	v_rcp_f32_e32 v126, v126
	v_add_f32_e32 v127, 1.0, v155
	v_mul_f32_e32 v155, 0xbfb8aa3b, v122
	v_rcp_f32_e32 v127, v127
	v_exp_f32_e32 v155, v155
	v_mul_f32_e32 v126, v128, v126
	v_mul_f32_e32 v126, v126, v120
	v_mul_f32_e32 v120, v129, v127
	v_add_f32_e32 v127, 1.0, v155
	v_rcp_f32_e32 v127, v127
	v_mul_f32_e32 v128, 0xbfb8aa3b, v123
	v_mul_f32_e32 v129, v120, v121
	v_exp_f32_e32 v128, v128
	v_mul_f32_e32 v120, v122, v127
	v_mul_f32_e32 v122, v120, v114
	v_mul_f32_e32 v120, 0xbfb8aa3b, v124
	v_exp_f32_e32 v120, v120
	v_mul_f32_e32 v121, 0xbfb8aa3b, v125
	v_exp_f32_e32 v121, v121
	v_add_f32_e32 v114, 1.0, v128
	v_rcp_f32_e32 v114, v114
	v_add_f32_e32 v120, 1.0, v120
	v_rcp_f32_e32 v120, v120
	v_add_f32_e32 v121, 1.0, v121
	v_rcp_f32_e32 v121, v121
	v_mul_f32_e32 v114, v123, v114
	v_mul_f32_e32 v123, v114, v115
	v_mul_f32_e32 v114, v124, v120
	v_ashrrev_i32_e32 v157, 31, v156
	v_mov_b64_e32 v[146:147], s[72:73]
	v_mul_f32_e32 v124, v114, v116
	v_mul_f32_e32 v114, v125, v121
	v_mad_i64_i32 v[158:159], s[28:29], v154, s47, v[146:147]
	v_mul_f32_e32 v125, v114, v117
	v_lshlrev_b64 v[114:115], 1, v[156:157]
	v_lshl_add_u64 v[120:121], v[158:159], 0, v[114:115]
	v_cvt_pk_bf16_f32 v116, v118, v119
	v_cvt_pk_bf16_f32 v117, v126, v129
	v_cvt_pk_bf16_f32 v118, v122, v123
	v_cvt_pk_bf16_f32 v119, v124, v125
	global_store_dwordx4 v[120:121], v[116:119], off nt
	s_andn2_b64 vcc, exec, s[0:1]
	s_mov_b64 s[0:1], -1
	v_mul_f32_e32 v116, 0xbfb8aa3b, v110
	v_exp_f32_e32 v116, v116
	v_mul_f32_e32 v117, 0xbfb8aa3b, v111
	v_exp_f32_e32 v117, v117
	v_or_b32_e32 v118, 16, v154
	v_add_f32_e32 v116, 1.0, v116
	v_rcp_f32_e32 v119, v116
	v_add_f32_e32 v116, 1.0, v117
	v_rcp_f32_e32 v120, v116
	v_mad_i64_i32 v[116:117], s[28:29], v118, s47, v[146:147]
	v_mul_f32_e32 v110, v110, v119
	v_mul_f32_e32 v110, v110, v102
	v_mul_f32_e32 v102, v111, v120
	v_mul_f32_e32 v111, 0xbfb8aa3b, v112
	v_exp_f32_e32 v111, v111
	v_mul_f32_e32 v118, 0xbfb8aa3b, v113
	v_exp_f32_e32 v118, v118
	v_mul_f32_e32 v119, v102, v103
	v_add_f32_e32 v102, 1.0, v111
	v_rcp_f32_e32 v102, v102
	v_add_f32_e32 v103, 1.0, v118
	v_mul_f32_e32 v111, 0xbfb8aa3b, v106
	v_rcp_f32_e32 v103, v103
	v_exp_f32_e32 v111, v111
	v_mul_f32_e32 v102, v112, v102
	v_mul_f32_e32 v104, v102, v104
	v_mul_f32_e32 v102, v113, v103
	v_add_f32_e32 v103, 1.0, v111
	v_rcp_f32_e32 v103, v103
	v_mul_f32_e32 v111, 0xbfb8aa3b, v107
	v_mul_f32_e32 v105, v102, v105
	v_exp_f32_e32 v111, v111
	v_mul_f32_e32 v102, v106, v103
	v_mul_f32_e32 v106, v102, v98
	v_mul_f32_e32 v102, 0xbfb8aa3b, v108
	v_exp_f32_e32 v102, v102
	v_mul_f32_e32 v103, 0xbfb8aa3b, v109
	v_exp_f32_e32 v103, v103
	v_add_f32_e32 v98, 1.0, v111
	v_rcp_f32_e32 v98, v98
	v_add_f32_e32 v102, 1.0, v102
	v_rcp_f32_e32 v102, v102
	v_add_f32_e32 v103, 1.0, v103
	v_rcp_f32_e32 v103, v103
	v_mul_f32_e32 v98, v107, v98
	v_mul_f32_e32 v107, v98, v99
	v_mul_f32_e32 v98, v108, v102
	v_mul_f32_e32 v108, v98, v100
	v_mul_f32_e32 v98, v109, v103
	v_mul_f32_e32 v101, v98, v101
	v_lshl_add_u64 v[102:103], v[116:117], 0, v[114:115]
	v_cvt_pk_bf16_f32 v98, v110, v119
	v_cvt_pk_bf16_f32 v99, v104, v105
	v_cvt_pk_bf16_f32 v100, v106, v107
	v_cvt_pk_bf16_f32 v101, v108, v101
	global_store_dwordx4 v[102:103], v[98:101], off nt
	s_nop 1
	v_mul_f32_e32 v98, 0xbfb8aa3b, v94
	v_exp_f32_e32 v98, v98
	v_mul_f32_e32 v99, 0xbfb8aa3b, v95
	v_exp_f32_e32 v99, v99
	v_or_b32_e32 v100, 32, v154
	v_add_f32_e32 v98, 1.0, v98
	v_rcp_f32_e32 v101, v98
	v_add_f32_e32 v98, 1.0, v99
	v_rcp_f32_e32 v102, v98
	v_mad_i64_i32 v[98:99], s[28:29], v100, s47, v[146:147]
	v_mul_f32_e32 v94, v94, v101
	v_mul_f32_e32 v94, v94, v86
	v_mul_f32_e32 v86, v95, v102
	v_mul_f32_e32 v95, 0xbfb8aa3b, v96
	v_exp_f32_e32 v95, v95
	v_mul_f32_e32 v100, 0xbfb8aa3b, v97
	v_exp_f32_e32 v100, v100
	v_mul_f32_e32 v101, v86, v87
	v_add_f32_e32 v86, 1.0, v95
	v_rcp_f32_e32 v86, v86
	v_add_f32_e32 v87, 1.0, v100
	v_mul_f32_e32 v95, 0xbfb8aa3b, v90
	v_rcp_f32_e32 v87, v87
	v_exp_f32_e32 v95, v95
	v_mul_f32_e32 v86, v96, v86
	v_mul_f32_e32 v88, v86, v88
	v_mul_f32_e32 v86, v97, v87
	v_add_f32_e32 v87, 1.0, v95
	v_rcp_f32_e32 v87, v87
	v_mul_f32_e32 v95, 0xbfb8aa3b, v91
	v_mul_f32_e32 v89, v86, v89
	v_exp_f32_e32 v95, v95
	v_mul_f32_e32 v86, v90, v87
	v_mul_f32_e32 v90, v86, v82
	v_mul_f32_e32 v86, 0xbfb8aa3b, v92
	v_exp_f32_e32 v86, v86
	v_mul_f32_e32 v87, 0xbfb8aa3b, v93
	v_exp_f32_e32 v87, v87
	v_add_f32_e32 v82, 1.0, v95
	v_rcp_f32_e32 v82, v82
	v_add_f32_e32 v86, 1.0, v86
	v_rcp_f32_e32 v86, v86
	v_add_f32_e32 v87, 1.0, v87
	v_rcp_f32_e32 v87, v87
	v_mul_f32_e32 v82, v91, v82
	v_mul_f32_e32 v91, v82, v83
	v_mul_f32_e32 v82, v92, v86
	v_mul_f32_e32 v92, v82, v84
	v_mul_f32_e32 v82, v93, v87
	v_mul_f32_e32 v85, v82, v85
	v_lshl_add_u64 v[86:87], v[98:99], 0, v[114:115]
	v_cvt_pk_bf16_f32 v82, v94, v101
	v_cvt_pk_bf16_f32 v83, v88, v89
	v_cvt_pk_bf16_f32 v84, v90, v91
	v_cvt_pk_bf16_f32 v85, v92, v85
	global_store_dwordx4 v[86:87], v[82:85], off nt
	s_nop 1
	v_mul_f32_e32 v82, 0xbfb8aa3b, v78
	v_exp_f32_e32 v82, v82
	v_mul_f32_e32 v83, 0xbfb8aa3b, v79
; __device__ __forceinline__ unsigned cvt_pk_bf16(float lo, float hi) { unsigned r; asm volatile("v_cvt_pk_bf16_f32 %0, %1, %2" : "=v"(r) : "v"(lo), "v"(hi)); return r; }
; __device__ __forceinline__ float sigm(float x) { return __builtin_amdgcn_rcpf(1.0f + __expf(-x)); }
;     __device__ __forceinline__ void operator()(const f32x4 (&acc)[2][2][4][2], const Unit& u, int wr, int wc, int fr, int fq) const {
;     ...
;             for (int m = 0; m < 4; ++m) { bf16_t* rowp = H + (size_t)(row0 + ai * HALF + m * 16) * ldc + col0;
;                 float o[8];
; #pragma unroll
;                 for (int n = 0; n < 2; ++n)
; #pragma unroll
;                     for (int i = 0; i < 4; ++i) { const float a = acc[ai][0][m][n][i], g = acc[ai][1][m][n][i]; o[4 * n + i] = a * sigm(a) * g; }
;                 u32x4 w; w.x = cvt_pk_bf16(o[0], o[1]); w.y = cvt_pk_bf16(o[2], o[3]); w.z = cvt_pk_bf16(o[4], o[5]); w.w = cvt_pk_bf16(o[6], o[7]);
;                 *(u32x4*)rowp = w; }
	v_exp_f32_e32 v83, v83
	v_or_b32_e32 v84, 48, v154
	v_add_f32_e32 v82, 1.0, v82
	v_rcp_f32_e32 v85, v82
	v_add_f32_e32 v82, 1.0, v83
	v_rcp_f32_e32 v86, v82
	v_mad_i64_i32 v[82:83], s[28:29], v84, s47, v[146:147]
	v_mul_f32_e32 v78, v78, v85
	v_mul_f32_e32 v78, v78, v70
	v_mul_f32_e32 v70, v79, v86
	v_mul_f32_e32 v79, 0xbfb8aa3b, v80
	v_exp_f32_e32 v79, v79
	v_mul_f32_e32 v84, 0xbfb8aa3b, v81
	v_exp_f32_e32 v84, v84
	v_mul_f32_e32 v85, v70, v71
	v_add_f32_e32 v70, 1.0, v79
	v_rcp_f32_e32 v70, v70
	v_add_f32_e32 v71, 1.0, v84
	v_mul_f32_e32 v79, 0xbfb8aa3b, v74
	v_rcp_f32_e32 v71, v71
	v_exp_f32_e32 v79, v79
	v_mul_f32_e32 v70, v80, v70
	v_mul_f32_e32 v72, v70, v72
	v_mul_f32_e32 v70, v81, v71
	v_add_f32_e32 v71, 1.0, v79
	v_rcp_f32_e32 v71, v71
	v_mul_f32_e32 v79, 0xbfb8aa3b, v75
	v_mul_f32_e32 v73, v70, v73
	v_exp_f32_e32 v79, v79
	v_mul_f32_e32 v70, v74, v71
	v_mul_f32_e32 v74, v70, v66
	v_mul_f32_e32 v70, 0xbfb8aa3b, v76
	v_exp_f32_e32 v70, v70
	v_mul_f32_e32 v71, 0xbfb8aa3b, v77
	v_exp_f32_e32 v71, v71
	v_add_f32_e32 v66, 1.0, v79
	v_rcp_f32_e32 v66, v66
	v_add_f32_e32 v70, 1.0, v70
	v_rcp_f32_e32 v70, v70
	v_add_f32_e32 v71, 1.0, v71
	v_rcp_f32_e32 v71, v71
	v_mul_f32_e32 v66, v75, v66
	v_mul_f32_e32 v75, v66, v67
	v_mul_f32_e32 v66, v76, v70
	v_mul_f32_e32 v76, v66, v68
	v_mul_f32_e32 v66, v77, v71
	v_mul_f32_e32 v69, v66, v69
	v_lshl_add_u64 v[70:71], v[82:83], 0, v[114:115]
	v_cvt_pk_bf16_f32 v66, v78, v85
	v_cvt_pk_bf16_f32 v67, v72, v73
	v_cvt_pk_bf16_f32 v68, v74, v75
	v_cvt_pk_bf16_f32 v69, v76, v69
	global_store_dwordx4 v[70:71], v[66:69], off nt
	s_nop 1
	v_mul_f32_e32 v66, 0xbfb8aa3b, v62
	v_exp_f32_e32 v66, v66
	v_mul_f32_e32 v67, 0xbfb8aa3b, v63
	v_exp_f32_e32 v67, v67
	v_add_u32_e32 v68, 0x80, v154
	v_add_f32_e32 v66, 1.0, v66
	v_rcp_f32_e32 v69, v66
	v_add_f32_e32 v66, 1.0, v67
	v_rcp_f32_e32 v70, v66
	v_mad_i64_i32 v[66:67], s[28:29], v68, s47, v[146:147]
	v_mul_f32_e32 v62, v62, v69
	v_mul_f32_e32 v62, v62, v54
	v_mul_f32_e32 v54, v63, v70
	v_mul_f32_e32 v63, 0xbfb8aa3b, v64
	v_exp_f32_e32 v63, v63
	v_mul_f32_e32 v68, 0xbfb8aa3b, v65
	v_exp_f32_e32 v68, v68
	v_mul_f32_e32 v69, v54, v55
	v_add_f32_e32 v54, 1.0, v63
	v_rcp_f32_e32 v54, v54
	v_add_f32_e32 v55, 1.0, v68
	v_mul_f32_e32 v63, 0xbfb8aa3b, v58
	v_rcp_f32_e32 v55, v55
	v_exp_f32_e32 v63, v63
	v_mul_f32_e32 v54, v64, v54
	v_mul_f32_e32 v56, v54, v56
	v_mul_f32_e32 v54, v65, v55
	v_add_f32_e32 v55, 1.0, v63
	v_rcp_f32_e32 v55, v55
	v_mul_f32_e32 v63, 0xbfb8aa3b, v59
	v_mul_f32_e32 v57, v54, v57
	v_exp_f32_e32 v63, v63
	v_mul_f32_e32 v54, v58, v55
	v_mul_f32_e32 v58, v54, v50
	v_mul_f32_e32 v54, 0xbfb8aa3b, v60
	v_exp_f32_e32 v54, v54
	v_mul_f32_e32 v55, 0xbfb8aa3b, v61
	v_exp_f32_e32 v55, v55
	v_add_f32_e32 v50, 1.0, v63
	v_rcp_f32_e32 v50, v50
	v_add_f32_e32 v54, 1.0, v54
	v_rcp_f32_e32 v54, v54
	v_add_f32_e32 v55, 1.0, v55
	v_rcp_f32_e32 v55, v55
	v_mul_f32_e32 v50, v59, v50
	v_mul_f32_e32 v59, v50, v51
	v_mul_f32_e32 v50, v60, v54
	v_mul_f32_e32 v60, v50, v52
	v_mul_f32_e32 v50, v61, v55
	v_mul_f32_e32 v53, v50, v53
	v_lshl_add_u64 v[54:55], v[66:67], 0, v[114:115]
	v_cvt_pk_bf16_f32 v50, v62, v69
	v_cvt_pk_bf16_f32 v51, v56, v57
	v_cvt_pk_bf16_f32 v52, v58, v59
	v_cvt_pk_bf16_f32 v53, v60, v53
	global_store_dwordx4 v[54:55], v[50:53], off nt
	s_nop 1
	v_mul_f32_e32 v50, 0xbfb8aa3b, v46
	v_exp_f32_e32 v50, v50
	v_mul_f32_e32 v51, 0xbfb8aa3b, v47
	v_exp_f32_e32 v51, v51
	v_add_u32_e32 v52, 0x90, v154
	v_add_f32_e32 v50, 1.0, v50
	v_rcp_f32_e32 v53, v50
	v_add_f32_e32 v50, 1.0, v51
	v_rcp_f32_e32 v54, v50
	v_mad_i64_i32 v[50:51], s[28:29], v52, s47, v[146:147]
	v_mul_f32_e32 v46, v46, v53
	v_mul_f32_e32 v46, v46, v38
	v_mul_f32_e32 v38, v47, v54
	v_mul_f32_e32 v47, 0xbfb8aa3b, v48
	v_exp_f32_e32 v47, v47
	v_mul_f32_e32 v52, 0xbfb8aa3b, v49
	v_exp_f32_e32 v52, v52
	v_mul_f32_e32 v53, v38, v39
	v_add_f32_e32 v38, 1.0, v47
	v_rcp_f32_e32 v38, v38
	v_add_f32_e32 v39, 1.0, v52
	v_mul_f32_e32 v47, 0xbfb8aa3b, v42
	v_rcp_f32_e32 v39, v39
	v_exp_f32_e32 v47, v47
	v_mul_f32_e32 v38, v48, v38
	v_mul_f32_e32 v40, v38, v40
	v_mul_f32_e32 v38, v49, v39
	v_add_f32_e32 v39, 1.0, v47
	v_rcp_f32_e32 v39, v39
	v_mul_f32_e32 v47, 0xbfb8aa3b, v43
	v_mul_f32_e32 v41, v38, v41
; __device__ __forceinline__ unsigned cvt_pk_bf16(float lo, float hi) { unsigned r; asm volatile("v_cvt_pk_bf16_f32 %0, %1, %2" : "=v"(r) : "v"(lo), "v"(hi)); return r; }
; __device__ __forceinline__ float sigm(float x) { return __builtin_amdgcn_rcpf(1.0f + __expf(-x)); }
;     __device__ __forceinline__ void operator()(const f32x4 (&acc)[2][2][4][2], const Unit& u, int wr, int wc, int fr, int fq) const {
;     ...
;             for (int m = 0; m < 4; ++m) { bf16_t* rowp = H + (size_t)(row0 + ai * HALF + m * 16) * ldc + col0;
;                 float o[8];
; #pragma unroll
;                 for (int n = 0; n < 2; ++n)
; #pragma unroll
;                     for (int i = 0; i < 4; ++i) { const float a = acc[ai][0][m][n][i], g = acc[ai][1][m][n][i]; o[4 * n + i] = a * sigm(a) * g; }
;                 u32x4 w; w.x = cvt_pk_bf16(o[0], o[1]); w.y = cvt_pk_bf16(o[2], o[3]); w.z = cvt_pk_bf16(o[4], o[5]); w.w = cvt_pk_bf16(o[6], o[7]);
;                 *(u32x4*)rowp = w; }
	v_exp_f32_e32 v47, v47
	v_mul_f32_e32 v38, v42, v39
	v_mul_f32_e32 v42, v38, v34
	v_mul_f32_e32 v38, 0xbfb8aa3b, v44
	v_exp_f32_e32 v38, v38
	v_mul_f32_e32 v39, 0xbfb8aa3b, v45
	v_exp_f32_e32 v39, v39
	v_add_f32_e32 v34, 1.0, v47
	v_rcp_f32_e32 v34, v34
	v_add_f32_e32 v38, 1.0, v38
	v_rcp_f32_e32 v38, v38
	v_add_f32_e32 v39, 1.0, v39
	v_rcp_f32_e32 v39, v39
	v_mul_f32_e32 v34, v43, v34
	v_mul_f32_e32 v43, v34, v35
	v_mul_f32_e32 v34, v44, v38
	v_mul_f32_e32 v44, v34, v36
	v_mul_f32_e32 v34, v45, v39
	v_mul_f32_e32 v37, v34, v37
	v_lshl_add_u64 v[38:39], v[50:51], 0, v[114:115]
	v_cvt_pk_bf16_f32 v34, v46, v53
	v_cvt_pk_bf16_f32 v35, v40, v41
	v_cvt_pk_bf16_f32 v36, v42, v43
	v_cvt_pk_bf16_f32 v37, v44, v37
	global_store_dwordx4 v[38:39], v[34:37], off nt
	s_nop 1
	v_mul_f32_e32 v34, 0xbfb8aa3b, v30
	v_exp_f32_e32 v34, v34
	v_mul_f32_e32 v35, 0xbfb8aa3b, v31
	v_exp_f32_e32 v35, v35
	v_add_u32_e32 v36, 0xa0, v154
	v_add_f32_e32 v34, 1.0, v34
	v_rcp_f32_e32 v37, v34
	v_add_f32_e32 v34, 1.0, v35
	v_rcp_f32_e32 v38, v34
	v_mad_i64_i32 v[34:35], s[28:29], v36, s47, v[146:147]
	v_mul_f32_e32 v30, v30, v37
	v_mul_f32_e32 v30, v30, v22
	v_mul_f32_e32 v22, v31, v38
	v_mul_f32_e32 v31, 0xbfb8aa3b, v32
	v_exp_f32_e32 v31, v31
	v_mul_f32_e32 v36, 0xbfb8aa3b, v33
	v_exp_f32_e32 v36, v36
	v_mul_f32_e32 v37, v22, v23
	v_add_f32_e32 v22, 1.0, v31
	v_rcp_f32_e32 v22, v22
	v_add_f32_e32 v23, 1.0, v36
	v_mul_f32_e32 v31, 0xbfb8aa3b, v26
	v_rcp_f32_e32 v23, v23
	v_exp_f32_e32 v31, v31
	v_mul_f32_e32 v22, v32, v22
	v_mul_f32_e32 v24, v22, v24
	v_mul_f32_e32 v22, v33, v23
	v_add_f32_e32 v23, 1.0, v31
	v_rcp_f32_e32 v23, v23
	v_mul_f32_e32 v31, 0xbfb8aa3b, v27
	v_mul_f32_e32 v25, v22, v25
	v_exp_f32_e32 v31, v31
	v_mul_f32_e32 v22, v26, v23
	v_mul_f32_e32 v26, v22, v18
	v_mul_f32_e32 v22, 0xbfb8aa3b, v28
	v_exp_f32_e32 v22, v22
	v_mul_f32_e32 v23, 0xbfb8aa3b, v29
	v_exp_f32_e32 v23, v23
	v_add_f32_e32 v18, 1.0, v31
	v_rcp_f32_e32 v18, v18
	v_add_f32_e32 v22, 1.0, v22
	v_rcp_f32_e32 v22, v22
	v_add_f32_e32 v23, 1.0, v23
	v_rcp_f32_e32 v23, v23
	v_mul_f32_e32 v18, v27, v18
	v_mul_f32_e32 v27, v18, v19
	v_mul_f32_e32 v18, v28, v22
	v_mul_f32_e32 v28, v18, v20
	v_mul_f32_e32 v18, v29, v23
	v_mul_f32_e32 v21, v18, v21
	v_lshl_add_u64 v[22:23], v[34:35], 0, v[114:115]
	v_cvt_pk_bf16_f32 v18, v30, v37
	v_cvt_pk_bf16_f32 v19, v24, v25
	v_cvt_pk_bf16_f32 v20, v26, v27
	v_cvt_pk_bf16_f32 v21, v28, v21
	global_store_dwordx4 v[22:23], v[18:21], off nt
	s_nop 1
	v_mul_f32_e32 v18, 0xbfb8aa3b, v14
	v_exp_f32_e32 v18, v18
	v_mul_f32_e32 v19, 0xbfb8aa3b, v15
	v_exp_f32_e32 v19, v19
	v_add_u32_e32 v20, 0xb0, v154
	v_add_f32_e32 v18, 1.0, v18
	v_rcp_f32_e32 v21, v18
	v_add_f32_e32 v18, 1.0, v19
	v_rcp_f32_e32 v22, v18
	v_mad_i64_i32 v[18:19], s[28:29], v20, s47, v[146:147]
	v_mul_f32_e32 v14, v14, v21
	v_mul_f32_e32 v14, v14, v6
	v_mul_f32_e32 v6, v15, v22
	v_mul_f32_e32 v15, 0xbfb8aa3b, v16
	v_exp_f32_e32 v15, v15
	v_mul_f32_e32 v20, 0xbfb8aa3b, v17
	v_exp_f32_e32 v20, v20
	v_mul_f32_e32 v21, v6, v7
	v_add_f32_e32 v6, 1.0, v15
	v_rcp_f32_e32 v6, v6
	v_add_f32_e32 v7, 1.0, v20
	v_mul_f32_e32 v15, 0xbfb8aa3b, v10
	v_rcp_f32_e32 v7, v7
	v_exp_f32_e32 v15, v15
	v_mul_f32_e32 v6, v16, v6
	v_mul_f32_e32 v8, v6, v8
	v_mul_f32_e32 v6, v17, v7
	v_add_f32_e32 v7, 1.0, v15
	v_rcp_f32_e32 v7, v7
	v_mul_f32_e32 v15, 0xbfb8aa3b, v11
	v_mul_f32_e32 v9, v6, v9
	v_exp_f32_e32 v15, v15
	v_mul_f32_e32 v6, v10, v7
	v_mul_f32_e32 v10, v6, v2
	v_mul_f32_e32 v6, 0xbfb8aa3b, v12
	v_exp_f32_e32 v6, v6
	v_mul_f32_e32 v7, 0xbfb8aa3b, v13
	v_exp_f32_e32 v7, v7
	v_add_f32_e32 v2, 1.0, v15
	v_rcp_f32_e32 v2, v2
	v_add_f32_e32 v6, 1.0, v6
	v_rcp_f32_e32 v6, v6
	v_add_f32_e32 v7, 1.0, v7
	v_rcp_f32_e32 v7, v7
	v_mul_f32_e32 v2, v11, v2
	v_mul_f32_e32 v11, v2, v3
	v_mul_f32_e32 v2, v12, v6
	v_mul_f32_e32 v12, v2, v4
	v_mul_f32_e32 v2, v13, v7
	v_mul_f32_e32 v5, v2, v5
	v_lshl_add_u64 v[6:7], v[18:19], 0, v[114:115]
	v_cvt_pk_bf16_f32 v2, v14, v21
	v_cvt_pk_bf16_f32 v3, v8, v9
	v_cvt_pk_bf16_f32 v4, v10, v11
	v_cvt_pk_bf16_f32 v5, v12, v5
	global_store_dwordx4 v[6:7], v[2:5], off nt
	s_cbranch_vccnz .LBB0_1094
	s_andn2_b64 vcc, exec, s[6:7]
	s_cbranch_vccnz .LBB0_1093
	s_barrier
	s_branch .LBB0_1093
